# rotary epilogue of the in-projection GEMMs software-pipelined: table loads two row-groups ahead in 3 register buffers, counted vmcnt (stores not waited); 5 blocks (phases 1,5,16)
# speedup vs baseline: 1.0118x; 1.0056x over previous
.LBB0_200:
	s_and_b64 vcc, exec, s[4:5]
	s_cbranch_vccz .LBB0_205
	v_add_u32_e32 v128, s40, v146
	v_ashrrev_i32_e32 v129, 31, v128
	v_lshlrev_b64 v[128:129], 8, v[128:129]
	v_lshl_add_u64 v[132:133], v[150:151], 0, v[128:129]
	v_lshl_add_u64 v[134:135], v[152:153], 0, v[128:129]
	s_lshl_b32 s0, s31, 4
	s_lshl_b32 s31, s38, 1
	s_cmp_gt_u32 s38, 7
	s_mov_b64 s[4:5], -1
	v_lshl_add_u64 v[128:129], v[132:133], 0, s[18:19]
	v_lshl_add_u64 v[130:131], v[134:135], 0, s[18:19]
	s_cbranch_scc0 .LBB0_203
	s_and_b32 s4, s31, 14
	s_or_b32 s4, s0, s4
	s_or_b32 s4, s4, s92
	s_ashr_i32 s5, s4, 31
	s_lshl_b64 s[4:5], s[4:5], 21
	s_add_u32 s4, s58, s4
	s_addc_u32 s5, s22, s5
	s_lshl_b32 s33, s29, 8
	s_add_u32 s4, s4, s33
	s_addc_u32 s5, s5, 0
	s_add_u32 s4, s4, s12
	s_addc_u32 s5, s5, s13
	v_mov_b32_e32 v163, v145
	v_lshl_add_u64 v[168:169], s[4:5], 0, v[162:163]
	v_mov_b32_e32 v165, v145
	v_lshl_add_u64 v[172:173], v[168:169], 0, v[164:165]
	s_mov_b64 s[4:5], 0
	v_add_co_u32_e32 v192, vcc, 0x1000, v172
	s_nop 1
	v_addc_co_u32_e32 v193, vcc, 0, v173, vcc
	global_load_dwordx4 v[196:199], v[132:133], off
	global_load_dwordx4 v[200:203], v[132:133], off offset:16
	global_load_dwordx4 v[204:207], v[134:135], off
	global_load_dwordx4 v[208:211], v[134:135], off offset:16
	v_lshl_add_u64 v[132:133], v[132:133], 0, s[18:19]
	v_lshl_add_u64 v[134:135], v[134:135], 0, s[18:19]
	global_load_dwordx4 v[214:217], v[132:133], off
	global_load_dwordx4 v[218:221], v[132:133], off offset:16
	global_load_dwordx4 v[222:225], v[134:135], off
	global_load_dwordx4 v[226:229], v[134:135], off offset:16
	v_lshl_add_u64 v[132:133], v[132:133], 0, s[18:19]
	v_lshl_add_u64 v[134:135], v[134:135], 0, s[18:19]
	global_load_dwordx4 v[230:233], v[132:133], off
	global_load_dwordx4 v[234:237], v[132:133], off offset:16
	global_load_dwordx4 v[238:241], v[134:135], off
	global_load_dwordx4 v[242:245], v[134:135], off offset:16
	v_lshl_add_u64 v[132:133], v[132:133], 0, s[18:19]
	v_lshl_add_u64 v[134:135], v[134:135], 0, s[18:19]
	s_waitcnt vmcnt(8)
	v_pk_mul_f32 v[246:247], v[118:119], v[206:207]
	v_pk_mul_f32 v[248:249], v[116:117], v[204:205]
	v_pk_mul_f32 v[250:251], v[114:115], v[210:211]
	v_pk_mul_f32 v[252:253], v[112:113], v[208:209]
	v_pk_mul_f32 v[206:207], v[126:127], v[206:207]
	v_pk_mul_f32 v[204:205], v[124:125], v[204:205]
	v_pk_mul_f32 v[210:211], v[122:123], v[210:211]
	v_pk_mul_f32 v[208:209], v[120:121], v[208:209]
	v_pk_fma_f32 v[246:247], v[126:127], v[198:199], v[246:247] neg_lo:[0,0,1] neg_hi:[0,0,1]
	v_pk_fma_f32 v[248:249], v[124:125], v[196:197], v[248:249] neg_lo:[0,0,1] neg_hi:[0,0,1]
	v_pk_fma_f32 v[250:251], v[122:123], v[202:203], v[250:251] neg_lo:[0,0,1] neg_hi:[0,0,1]
	v_pk_fma_f32 v[252:253], v[120:121], v[200:201], v[252:253] neg_lo:[0,0,1] neg_hi:[0,0,1]
	v_pk_fma_f32 v[198:199], v[118:119], v[198:199], v[206:207]
	v_pk_fma_f32 v[196:197], v[116:117], v[196:197], v[204:205]
	v_pk_fma_f32 v[202:203], v[114:115], v[202:203], v[210:211]
	v_pk_fma_f32 v[200:201], v[112:113], v[200:201], v[208:209]
	v_cvt_pk_bf16_f32 v204, v248, v249
	v_cvt_pk_bf16_f32 v205, v246, v247
	v_cvt_pk_bf16_f32 v206, v252, v253
	v_cvt_pk_bf16_f32 v207, v250, v251
	v_cvt_pk_bf16_f32 v208, v196, v197
	v_cvt_pk_bf16_f32 v209, v198, v199
	v_cvt_pk_bf16_f32 v210, v200, v201
	v_cvt_pk_bf16_f32 v211, v202, v203
	global_store_dwordx4 v[172:173], v[204:207], off
	global_store_dwordx4 v[192:193], v[208:211], off
	v_lshl_add_u64 v[172:173], v[172:173], 0, s[14:15]
	v_lshl_add_u64 v[192:193], v[192:193], 0, s[14:15]
	global_load_dwordx4 v[196:199], v[132:133], off
	global_load_dwordx4 v[200:203], v[132:133], off offset:16
	global_load_dwordx4 v[204:207], v[134:135], off
	global_load_dwordx4 v[208:211], v[134:135], off offset:16
	v_lshl_add_u64 v[132:133], v[132:133], 0, s[24:25]
	v_lshl_add_u64 v[134:135], v[134:135], 0, s[24:25]
	s_waitcnt vmcnt(10)
	v_pk_mul_f32 v[246:247], v[102:103], v[224:225]
	v_pk_mul_f32 v[248:249], v[100:101], v[222:223]
	v_pk_mul_f32 v[250:251], v[98:99], v[228:229]
	v_pk_mul_f32 v[252:253], v[96:97], v[226:227]
	v_pk_mul_f32 v[224:225], v[110:111], v[224:225]
	v_pk_mul_f32 v[222:223], v[108:109], v[222:223]
	v_pk_mul_f32 v[228:229], v[106:107], v[228:229]
	v_pk_mul_f32 v[226:227], v[104:105], v[226:227]
	v_pk_fma_f32 v[246:247], v[110:111], v[216:217], v[246:247] neg_lo:[0,0,1] neg_hi:[0,0,1]
	v_pk_fma_f32 v[248:249], v[108:109], v[214:215], v[248:249] neg_lo:[0,0,1] neg_hi:[0,0,1]
	v_pk_fma_f32 v[250:251], v[106:107], v[220:221], v[250:251] neg_lo:[0,0,1] neg_hi:[0,0,1]
	v_pk_fma_f32 v[252:253], v[104:105], v[218:219], v[252:253] neg_lo:[0,0,1] neg_hi:[0,0,1]
	v_pk_fma_f32 v[216:217], v[102:103], v[216:217], v[224:225]
	v_pk_fma_f32 v[214:215], v[100:101], v[214:215], v[222:223]
	v_pk_fma_f32 v[220:221], v[98:99], v[220:221], v[228:229]
	v_pk_fma_f32 v[218:219], v[96:97], v[218:219], v[226:227]
	v_cvt_pk_bf16_f32 v222, v248, v249
	v_cvt_pk_bf16_f32 v223, v246, v247
	v_cvt_pk_bf16_f32 v224, v252, v253
	v_cvt_pk_bf16_f32 v225, v250, v251
	v_cvt_pk_bf16_f32 v226, v214, v215
	v_cvt_pk_bf16_f32 v227, v216, v217
	v_cvt_pk_bf16_f32 v228, v218, v219
	v_cvt_pk_bf16_f32 v229, v220, v221
	global_store_dwordx4 v[172:173], v[222:225], off
	global_store_dwordx4 v[192:193], v[226:229], off
	v_lshl_add_u64 v[172:173], v[172:173], 0, s[60:61]
	v_lshl_add_u64 v[192:193], v[192:193], 0, s[60:61]
	global_load_dwordx4 v[214:217], v[132:133], off
	global_load_dwordx4 v[218:221], v[132:133], off offset:16
	global_load_dwordx4 v[222:225], v[134:135], off
	global_load_dwordx4 v[226:229], v[134:135], off offset:16
	v_lshl_add_u64 v[132:133], v[132:133], 0, s[18:19]
	v_lshl_add_u64 v[134:135], v[134:135], 0, s[18:19]
	s_waitcnt vmcnt(12)
	v_pk_mul_f32 v[246:247], v[86:87], v[240:241]
	v_pk_mul_f32 v[248:249], v[84:85], v[238:239]
	v_pk_mul_f32 v[250:251], v[82:83], v[244:245]
	v_pk_mul_f32 v[252:253], v[80:81], v[242:243]
	v_pk_mul_f32 v[240:241], v[94:95], v[240:241]
	v_pk_mul_f32 v[238:239], v[92:93], v[238:239]
	v_pk_mul_f32 v[244:245], v[90:91], v[244:245]
	v_pk_mul_f32 v[242:243], v[88:89], v[242:243]
	v_pk_fma_f32 v[246:247], v[94:95], v[232:233], v[246:247] neg_lo:[0,0,1] neg_hi:[0,0,1]
	v_pk_fma_f32 v[248:249], v[92:93], v[230:231], v[248:249] neg_lo:[0,0,1] neg_hi:[0,0,1]
	v_pk_fma_f32 v[250:251], v[90:91], v[236:237], v[250:251] neg_lo:[0,0,1] neg_hi:[0,0,1]
	v_pk_fma_f32 v[252:253], v[88:89], v[234:235], v[252:253] neg_lo:[0,0,1] neg_hi:[0,0,1]
	v_pk_fma_f32 v[232:233], v[86:87], v[232:233], v[240:241]
	v_pk_fma_f32 v[230:231], v[84:85], v[230:231], v[238:239]
	v_pk_fma_f32 v[236:237], v[82:83], v[236:237], v[244:245]
	v_pk_fma_f32 v[234:235], v[80:81], v[234:235], v[242:243]
	v_cvt_pk_bf16_f32 v238, v248, v249
	v_cvt_pk_bf16_f32 v239, v246, v247
	v_cvt_pk_bf16_f32 v240, v252, v253
	v_cvt_pk_bf16_f32 v241, v250, v251
	v_cvt_pk_bf16_f32 v242, v230, v231
	v_cvt_pk_bf16_f32 v243, v232, v233
	v_cvt_pk_bf16_f32 v244, v234, v235
	v_cvt_pk_bf16_f32 v245, v236, v237
	global_store_dwordx4 v[172:173], v[238:241], off
	global_store_dwordx4 v[192:193], v[242:245], off
	v_lshl_add_u64 v[172:173], v[172:173], 0, s[14:15]
	v_lshl_add_u64 v[192:193], v[192:193], 0, s[14:15]
	global_load_dwordx4 v[230:233], v[132:133], off
	global_load_dwordx4 v[234:237], v[132:133], off offset:16
	global_load_dwordx4 v[238:241], v[134:135], off
	global_load_dwordx4 v[242:245], v[134:135], off offset:16
	v_lshl_add_u64 v[132:133], v[132:133], 0, s[18:19]
	v_lshl_add_u64 v[134:135], v[134:135], 0, s[18:19]
	s_waitcnt vmcnt(12)
	v_pk_mul_f32 v[246:247], v[70:71], v[206:207]
	v_pk_mul_f32 v[248:249], v[68:69], v[204:205]
	v_pk_mul_f32 v[250:251], v[66:67], v[210:211]
	v_pk_mul_f32 v[252:253], v[64:65], v[208:209]
	v_pk_mul_f32 v[206:207], v[78:79], v[206:207]
	v_pk_mul_f32 v[204:205], v[76:77], v[204:205]
	v_pk_mul_f32 v[210:211], v[74:75], v[210:211]
	v_pk_mul_f32 v[208:209], v[72:73], v[208:209]
	v_pk_fma_f32 v[246:247], v[78:79], v[198:199], v[246:247] neg_lo:[0,0,1] neg_hi:[0,0,1]
	v_pk_fma_f32 v[248:249], v[76:77], v[196:197], v[248:249] neg_lo:[0,0,1] neg_hi:[0,0,1]
	v_pk_fma_f32 v[250:251], v[74:75], v[202:203], v[250:251] neg_lo:[0,0,1] neg_hi:[0,0,1]
	v_pk_fma_f32 v[252:253], v[72:73], v[200:201], v[252:253] neg_lo:[0,0,1] neg_hi:[0,0,1]
	v_pk_fma_f32 v[198:199], v[70:71], v[198:199], v[206:207]
	v_pk_fma_f32 v[196:197], v[68:69], v[196:197], v[204:205]
	v_pk_fma_f32 v[202:203], v[66:67], v[202:203], v[210:211]
	v_pk_fma_f32 v[200:201], v[64:65], v[200:201], v[208:209]
	v_cvt_pk_bf16_f32 v204, v248, v249
	v_cvt_pk_bf16_f32 v205, v246, v247
	v_cvt_pk_bf16_f32 v206, v252, v253
	v_cvt_pk_bf16_f32 v207, v250, v251
	v_cvt_pk_bf16_f32 v208, v196, v197
	v_cvt_pk_bf16_f32 v209, v198, v199
	v_cvt_pk_bf16_f32 v210, v200, v201
	v_cvt_pk_bf16_f32 v211, v202, v203
	global_store_dwordx4 v[172:173], v[204:207], off
	global_store_dwordx4 v[192:193], v[208:211], off
	v_lshl_add_u64 v[172:173], v[172:173], 0, s[62:63]
	v_lshl_add_u64 v[192:193], v[192:193], 0, s[62:63]
	global_load_dwordx4 v[196:199], v[132:133], off
	global_load_dwordx4 v[200:203], v[132:133], off offset:16
	global_load_dwordx4 v[204:207], v[134:135], off
	global_load_dwordx4 v[208:211], v[134:135], off offset:16
	v_lshl_add_u64 v[132:133], v[132:133], 0, s[18:19]
	v_lshl_add_u64 v[134:135], v[134:135], 0, s[18:19]
	s_waitcnt vmcnt(12)
	v_pk_mul_f32 v[246:247], v[54:55], v[224:225]
	v_pk_mul_f32 v[248:249], v[52:53], v[222:223]
	v_pk_mul_f32 v[250:251], v[50:51], v[228:229]
	v_pk_mul_f32 v[252:253], v[48:49], v[226:227]
	v_pk_mul_f32 v[224:225], v[62:63], v[224:225]
	v_pk_mul_f32 v[222:223], v[60:61], v[222:223]
	v_pk_mul_f32 v[228:229], v[58:59], v[228:229]
	v_pk_mul_f32 v[226:227], v[56:57], v[226:227]
	v_pk_fma_f32 v[246:247], v[62:63], v[216:217], v[246:247] neg_lo:[0,0,1] neg_hi:[0,0,1]
	v_pk_fma_f32 v[248:249], v[60:61], v[214:215], v[248:249] neg_lo:[0,0,1] neg_hi:[0,0,1]
	v_pk_fma_f32 v[250:251], v[58:59], v[220:221], v[250:251] neg_lo:[0,0,1] neg_hi:[0,0,1]
	v_pk_fma_f32 v[252:253], v[56:57], v[218:219], v[252:253] neg_lo:[0,0,1] neg_hi:[0,0,1]
	v_pk_fma_f32 v[216:217], v[54:55], v[216:217], v[224:225]
	v_pk_fma_f32 v[214:215], v[52:53], v[214:215], v[222:223]
	v_pk_fma_f32 v[220:221], v[50:51], v[220:221], v[228:229]
	v_pk_fma_f32 v[218:219], v[48:49], v[218:219], v[226:227]
	v_cvt_pk_bf16_f32 v222, v248, v249
	v_cvt_pk_bf16_f32 v223, v246, v247
	v_cvt_pk_bf16_f32 v224, v252, v253
	v_cvt_pk_bf16_f32 v225, v250, v251
	v_cvt_pk_bf16_f32 v226, v214, v215
	v_cvt_pk_bf16_f32 v227, v216, v217
	v_cvt_pk_bf16_f32 v228, v218, v219
	v_cvt_pk_bf16_f32 v229, v220, v221
	global_store_dwordx4 v[172:173], v[222:225], off
	global_store_dwordx4 v[192:193], v[226:229], off
	v_lshl_add_u64 v[172:173], v[172:173], 0, s[14:15]
	v_lshl_add_u64 v[192:193], v[192:193], 0, s[14:15]
	global_load_dwordx4 v[214:217], v[132:133], off
	global_load_dwordx4 v[218:221], v[132:133], off offset:16
	global_load_dwordx4 v[222:225], v[134:135], off
	global_load_dwordx4 v[226:229], v[134:135], off offset:16
	s_waitcnt vmcnt(12)
	v_pk_mul_f32 v[246:247], v[38:39], v[240:241]
	v_pk_mul_f32 v[248:249], v[36:37], v[238:239]
	v_pk_mul_f32 v[250:251], v[34:35], v[244:245]
	v_pk_mul_f32 v[252:253], v[32:33], v[242:243]
	v_pk_mul_f32 v[240:241], v[46:47], v[240:241]
	v_pk_mul_f32 v[238:239], v[44:45], v[238:239]
	v_pk_mul_f32 v[244:245], v[42:43], v[244:245]
	v_pk_mul_f32 v[242:243], v[40:41], v[242:243]
	v_pk_fma_f32 v[246:247], v[46:47], v[232:233], v[246:247] neg_lo:[0,0,1] neg_hi:[0,0,1]
	v_pk_fma_f32 v[248:249], v[44:45], v[230:231], v[248:249] neg_lo:[0,0,1] neg_hi:[0,0,1]
	v_pk_fma_f32 v[250:251], v[42:43], v[236:237], v[250:251] neg_lo:[0,0,1] neg_hi:[0,0,1]
	v_pk_fma_f32 v[252:253], v[40:41], v[234:235], v[252:253] neg_lo:[0,0,1] neg_hi:[0,0,1]
	v_pk_fma_f32 v[232:233], v[38:39], v[232:233], v[240:241]
	v_pk_fma_f32 v[230:231], v[36:37], v[230:231], v[238:239]
	v_pk_fma_f32 v[236:237], v[34:35], v[236:237], v[244:245]
	v_pk_fma_f32 v[234:235], v[32:33], v[234:235], v[242:243]
	v_cvt_pk_bf16_f32 v238, v248, v249
	v_cvt_pk_bf16_f32 v239, v246, v247
	v_cvt_pk_bf16_f32 v240, v252, v253
	v_cvt_pk_bf16_f32 v241, v250, v251
	v_cvt_pk_bf16_f32 v242, v230, v231
	v_cvt_pk_bf16_f32 v243, v232, v233
	v_cvt_pk_bf16_f32 v244, v234, v235
	v_cvt_pk_bf16_f32 v245, v236, v237
	global_store_dwordx4 v[172:173], v[238:241], off
	global_store_dwordx4 v[192:193], v[242:245], off
	v_lshl_add_u64 v[172:173], v[172:173], 0, s[60:61]
	v_lshl_add_u64 v[192:193], v[192:193], 0, s[60:61]
	s_waitcnt vmcnt(8)
	v_pk_mul_f32 v[246:247], v[22:23], v[206:207]
	v_pk_mul_f32 v[248:249], v[20:21], v[204:205]
	v_pk_mul_f32 v[250:251], v[18:19], v[210:211]
	v_pk_mul_f32 v[252:253], v[16:17], v[208:209]
	v_pk_mul_f32 v[206:207], v[30:31], v[206:207]
	v_pk_mul_f32 v[204:205], v[28:29], v[204:205]
	v_pk_mul_f32 v[210:211], v[26:27], v[210:211]
	v_pk_mul_f32 v[208:209], v[24:25], v[208:209]
	v_pk_fma_f32 v[246:247], v[30:31], v[198:199], v[246:247] neg_lo:[0,0,1] neg_hi:[0,0,1]
	v_pk_fma_f32 v[248:249], v[28:29], v[196:197], v[248:249] neg_lo:[0,0,1] neg_hi:[0,0,1]
	v_pk_fma_f32 v[250:251], v[26:27], v[202:203], v[250:251] neg_lo:[0,0,1] neg_hi:[0,0,1]
	v_pk_fma_f32 v[252:253], v[24:25], v[200:201], v[252:253] neg_lo:[0,0,1] neg_hi:[0,0,1]
	v_pk_fma_f32 v[198:199], v[22:23], v[198:199], v[206:207]
	v_pk_fma_f32 v[196:197], v[20:21], v[196:197], v[204:205]
	v_pk_fma_f32 v[202:203], v[18:19], v[202:203], v[210:211]
	v_pk_fma_f32 v[200:201], v[16:17], v[200:201], v[208:209]
	v_cvt_pk_bf16_f32 v204, v248, v249
	v_cvt_pk_bf16_f32 v205, v246, v247
	v_cvt_pk_bf16_f32 v206, v252, v253
	v_cvt_pk_bf16_f32 v207, v250, v251
	v_cvt_pk_bf16_f32 v208, v196, v197
	v_cvt_pk_bf16_f32 v209, v198, v199
	v_cvt_pk_bf16_f32 v210, v200, v201
	v_cvt_pk_bf16_f32 v211, v202, v203
	global_store_dwordx4 v[172:173], v[204:207], off
	global_store_dwordx4 v[192:193], v[208:211], off
	v_lshl_add_u64 v[172:173], v[172:173], 0, s[14:15]
	v_lshl_add_u64 v[192:193], v[192:193], 0, s[14:15]
	s_waitcnt vmcnt(4)
	v_pk_mul_f32 v[246:247], v[6:7], v[224:225]
	v_pk_mul_f32 v[248:249], v[4:5], v[222:223]
	v_pk_mul_f32 v[250:251], v[2:3], v[228:229]
	v_pk_mul_f32 v[252:253], v[0:1], v[226:227]
	v_pk_mul_f32 v[224:225], v[14:15], v[224:225]
	v_pk_mul_f32 v[222:223], v[12:13], v[222:223]
	v_pk_mul_f32 v[228:229], v[10:11], v[228:229]
	v_pk_mul_f32 v[226:227], v[8:9], v[226:227]
	v_pk_fma_f32 v[246:247], v[14:15], v[216:217], v[246:247] neg_lo:[0,0,1] neg_hi:[0,0,1]
	v_pk_fma_f32 v[248:249], v[12:13], v[214:215], v[248:249] neg_lo:[0,0,1] neg_hi:[0,0,1]
	v_pk_fma_f32 v[250:251], v[10:11], v[220:221], v[250:251] neg_lo:[0,0,1] neg_hi:[0,0,1]
	v_pk_fma_f32 v[252:253], v[8:9], v[218:219], v[252:253] neg_lo:[0,0,1] neg_hi:[0,0,1]
	v_pk_fma_f32 v[216:217], v[6:7], v[216:217], v[224:225]
	v_pk_fma_f32 v[214:215], v[4:5], v[214:215], v[222:223]
	v_pk_fma_f32 v[220:221], v[2:3], v[220:221], v[228:229]
	v_pk_fma_f32 v[218:219], v[0:1], v[218:219], v[226:227]
	v_cvt_pk_bf16_f32 v222, v248, v249
	v_cvt_pk_bf16_f32 v223, v246, v247
	v_cvt_pk_bf16_f32 v224, v252, v253
	v_cvt_pk_bf16_f32 v225, v250, v251
	v_cvt_pk_bf16_f32 v226, v214, v215
	v_cvt_pk_bf16_f32 v227, v216, v217
	v_cvt_pk_bf16_f32 v228, v218, v219
	v_cvt_pk_bf16_f32 v229, v220, v221
	global_store_dwordx4 v[172:173], v[222:225], off
	global_store_dwordx4 v[192:193], v[226:229], off
.LBB0_203:
	s_andn2_b64 vcc, exec, s[4:5]
	s_cbranch_vccnz .LBB0_205
	s_or_b32 s0, s0, s31
	s_or_b32 s4, s0, s92
	s_ashr_i32 s5, s4, 31
	s_lshl_b64 s[4:5], s[4:5], 21
	v_add_u32_e32 v144, s29, v146
	s_add_u32 s4, s96, s4
	v_lshlrev_b64 v[172:173], 8, v[144:145]
	s_addc_u32 s5, s88, s5
	v_mov_b32_e32 v167, v145
	v_lshl_add_u64 v[172:173], s[4:5], 0, v[172:173]
	v_lshl_add_u64 v[172:173], v[172:173], 0, v[166:167]
	v_lshl_add_u64 v[184:185], v[172:173], 0, s[18:19]
	global_load_dwordx4 v[196:199], v[132:133], off
	global_load_dwordx4 v[200:203], v[132:133], off offset:16
	global_load_dwordx4 v[204:207], v[134:135], off
	global_load_dwordx4 v[208:211], v[134:135], off offset:16
	v_lshl_add_u64 v[132:133], v[132:133], 0, s[18:19]
	v_lshl_add_u64 v[134:135], v[134:135], 0, s[18:19]
	global_load_dwordx4 v[214:217], v[132:133], off
	global_load_dwordx4 v[218:221], v[132:133], off offset:16
	global_load_dwordx4 v[222:225], v[134:135], off
	global_load_dwordx4 v[226:229], v[134:135], off offset:16
	v_lshl_add_u64 v[132:133], v[132:133], 0, s[18:19]
	v_lshl_add_u64 v[134:135], v[134:135], 0, s[18:19]
	global_load_dwordx4 v[230:233], v[132:133], off
	global_load_dwordx4 v[234:237], v[132:133], off offset:16
	global_load_dwordx4 v[238:241], v[134:135], off
	global_load_dwordx4 v[242:245], v[134:135], off offset:16
	v_lshl_add_u64 v[132:133], v[132:133], 0, s[18:19]
	v_lshl_add_u64 v[134:135], v[134:135], 0, s[18:19]
	s_waitcnt vmcnt(8)
	v_pk_mul_f32 v[246:247], v[118:119], v[206:207]
	v_pk_mul_f32 v[248:249], v[116:117], v[204:205]
	v_pk_mul_f32 v[250:251], v[114:115], v[210:211]
	v_pk_mul_f32 v[252:253], v[112:113], v[208:209]
	v_pk_mul_f32 v[206:207], v[126:127], v[206:207]
	v_pk_mul_f32 v[204:205], v[124:125], v[204:205]
	v_pk_mul_f32 v[210:211], v[122:123], v[210:211]
	v_pk_mul_f32 v[208:209], v[120:121], v[208:209]
	v_pk_fma_f32 v[246:247], v[126:127], v[198:199], v[246:247] neg_lo:[0,0,1] neg_hi:[0,0,1]
	v_pk_fma_f32 v[248:249], v[124:125], v[196:197], v[248:249] neg_lo:[0,0,1] neg_hi:[0,0,1]
	v_pk_fma_f32 v[250:251], v[122:123], v[202:203], v[250:251] neg_lo:[0,0,1] neg_hi:[0,0,1]
	v_pk_fma_f32 v[252:253], v[120:121], v[200:201], v[252:253] neg_lo:[0,0,1] neg_hi:[0,0,1]
	v_pk_fma_f32 v[198:199], v[118:119], v[198:199], v[206:207]
	v_pk_fma_f32 v[196:197], v[116:117], v[196:197], v[204:205]
	v_pk_fma_f32 v[202:203], v[114:115], v[202:203], v[210:211]
	v_pk_fma_f32 v[200:201], v[112:113], v[200:201], v[208:209]
	v_pk_mul_f32 v[246:247], v[246:247], s[26:27] op_sel_hi:[1,0]
	v_pk_mul_f32 v[248:249], v[248:249], s[26:27] op_sel_hi:[1,0]
	v_pk_mul_f32 v[250:251], v[250:251], s[26:27] op_sel_hi:[1,0]
	v_pk_mul_f32 v[252:253], v[252:253], s[26:27] op_sel_hi:[1,0]
	v_pk_mul_f32 v[198:199], v[198:199], s[26:27] op_sel_hi:[1,0]
	v_pk_mul_f32 v[196:197], v[196:197], s[26:27] op_sel_hi:[1,0]
	v_pk_mul_f32 v[202:203], v[202:203], s[26:27] op_sel_hi:[1,0]
	v_pk_mul_f32 v[200:201], v[200:201], s[26:27] op_sel_hi:[1,0]
	v_cvt_pk_bf16_f32 v204, v248, v249
	v_cvt_pk_bf16_f32 v205, v246, v247
	v_cvt_pk_bf16_f32 v206, v252, v253
	v_cvt_pk_bf16_f32 v207, v250, v251
	v_cvt_pk_bf16_f32 v208, v196, v197
	v_cvt_pk_bf16_f32 v209, v198, v199
	v_cvt_pk_bf16_f32 v210, v200, v201
	v_cvt_pk_bf16_f32 v211, v202, v203
	global_store_dwordx4 v[172:173], v[204:207], off
	global_store_dwordx4 v[172:173], v[208:211], off offset:128
	v_lshl_add_u64 v[172:173], v[172:173], 0, s[18:19]
	global_load_dwordx4 v[196:199], v[132:133], off
	global_load_dwordx4 v[200:203], v[132:133], off offset:16
	global_load_dwordx4 v[204:207], v[134:135], off
	global_load_dwordx4 v[208:211], v[134:135], off offset:16
	v_lshl_add_u64 v[132:133], v[132:133], 0, s[24:25]
	v_lshl_add_u64 v[134:135], v[134:135], 0, s[24:25]
	s_waitcnt vmcnt(10)
	v_pk_mul_f32 v[246:247], v[102:103], v[224:225]
	v_pk_mul_f32 v[248:249], v[100:101], v[222:223]
	v_pk_mul_f32 v[250:251], v[98:99], v[228:229]
	v_pk_mul_f32 v[252:253], v[96:97], v[226:227]
	v_pk_mul_f32 v[224:225], v[110:111], v[224:225]
	v_pk_mul_f32 v[222:223], v[108:109], v[222:223]
	v_pk_mul_f32 v[228:229], v[106:107], v[228:229]
	v_pk_mul_f32 v[226:227], v[104:105], v[226:227]
	v_pk_fma_f32 v[246:247], v[110:111], v[216:217], v[246:247] neg_lo:[0,0,1] neg_hi:[0,0,1]
	v_pk_fma_f32 v[248:249], v[108:109], v[214:215], v[248:249] neg_lo:[0,0,1] neg_hi:[0,0,1]
	v_pk_fma_f32 v[250:251], v[106:107], v[220:221], v[250:251] neg_lo:[0,0,1] neg_hi:[0,0,1]
	v_pk_fma_f32 v[252:253], v[104:105], v[218:219], v[252:253] neg_lo:[0,0,1] neg_hi:[0,0,1]
	v_pk_fma_f32 v[216:217], v[102:103], v[216:217], v[224:225]
	v_pk_fma_f32 v[214:215], v[100:101], v[214:215], v[222:223]
	v_pk_fma_f32 v[220:221], v[98:99], v[220:221], v[228:229]
	v_pk_fma_f32 v[218:219], v[96:97], v[218:219], v[226:227]
	v_pk_mul_f32 v[246:247], v[246:247], s[26:27] op_sel_hi:[1,0]
	v_pk_mul_f32 v[248:249], v[248:249], s[26:27] op_sel_hi:[1,0]
	v_pk_mul_f32 v[250:251], v[250:251], s[26:27] op_sel_hi:[1,0]
	v_pk_mul_f32 v[252:253], v[252:253], s[26:27] op_sel_hi:[1,0]
	v_pk_mul_f32 v[216:217], v[216:217], s[26:27] op_sel_hi:[1,0]
	v_pk_mul_f32 v[214:215], v[214:215], s[26:27] op_sel_hi:[1,0]
	v_pk_mul_f32 v[220:221], v[220:221], s[26:27] op_sel_hi:[1,0]
	v_pk_mul_f32 v[218:219], v[218:219], s[26:27] op_sel_hi:[1,0]
	v_cvt_pk_bf16_f32 v222, v248, v249
	v_cvt_pk_bf16_f32 v223, v246, v247
	v_cvt_pk_bf16_f32 v224, v252, v253
	v_cvt_pk_bf16_f32 v225, v250, v251
	v_cvt_pk_bf16_f32 v226, v214, v215
	v_cvt_pk_bf16_f32 v227, v216, v217
	v_cvt_pk_bf16_f32 v228, v218, v219
	v_cvt_pk_bf16_f32 v229, v220, v221
	global_store_dwordx4 v[172:173], v[222:225], off
	global_store_dwordx4 v[172:173], v[226:229], off offset:128
	v_lshl_add_u64 v[172:173], v[172:173], 0, s[18:19]
	global_load_dwordx4 v[214:217], v[132:133], off
	global_load_dwordx4 v[218:221], v[132:133], off offset:16
	global_load_dwordx4 v[222:225], v[134:135], off
	global_load_dwordx4 v[226:229], v[134:135], off offset:16
	v_lshl_add_u64 v[132:133], v[132:133], 0, s[18:19]
	v_lshl_add_u64 v[134:135], v[134:135], 0, s[18:19]
	s_waitcnt vmcnt(12)
	v_pk_mul_f32 v[246:247], v[86:87], v[240:241]
	v_pk_mul_f32 v[248:249], v[84:85], v[238:239]
	v_pk_mul_f32 v[250:251], v[82:83], v[244:245]
	v_pk_mul_f32 v[252:253], v[80:81], v[242:243]
	v_pk_mul_f32 v[240:241], v[94:95], v[240:241]
	v_pk_mul_f32 v[238:239], v[92:93], v[238:239]
	v_pk_mul_f32 v[244:245], v[90:91], v[244:245]
	v_pk_mul_f32 v[242:243], v[88:89], v[242:243]
	v_pk_fma_f32 v[246:247], v[94:95], v[232:233], v[246:247] neg_lo:[0,0,1] neg_hi:[0,0,1]
	v_pk_fma_f32 v[248:249], v[92:93], v[230:231], v[248:249] neg_lo:[0,0,1] neg_hi:[0,0,1]
	v_pk_fma_f32 v[250:251], v[90:91], v[236:237], v[250:251] neg_lo:[0,0,1] neg_hi:[0,0,1]
	v_pk_fma_f32 v[252:253], v[88:89], v[234:235], v[252:253] neg_lo:[0,0,1] neg_hi:[0,0,1]
	v_pk_fma_f32 v[232:233], v[86:87], v[232:233], v[240:241]
	v_pk_fma_f32 v[230:231], v[84:85], v[230:231], v[238:239]
	v_pk_fma_f32 v[236:237], v[82:83], v[236:237], v[244:245]
	v_pk_fma_f32 v[234:235], v[80:81], v[234:235], v[242:243]
	v_pk_mul_f32 v[246:247], v[246:247], s[26:27] op_sel_hi:[1,0]
	v_pk_mul_f32 v[248:249], v[248:249], s[26:27] op_sel_hi:[1,0]
	v_pk_mul_f32 v[250:251], v[250:251], s[26:27] op_sel_hi:[1,0]
	v_pk_mul_f32 v[252:253], v[252:253], s[26:27] op_sel_hi:[1,0]
	v_pk_mul_f32 v[232:233], v[232:233], s[26:27] op_sel_hi:[1,0]
	v_pk_mul_f32 v[230:231], v[230:231], s[26:27] op_sel_hi:[1,0]
	v_pk_mul_f32 v[236:237], v[236:237], s[26:27] op_sel_hi:[1,0]
	v_pk_mul_f32 v[234:235], v[234:235], s[26:27] op_sel_hi:[1,0]
	v_cvt_pk_bf16_f32 v238, v248, v249
	v_cvt_pk_bf16_f32 v239, v246, v247
	v_cvt_pk_bf16_f32 v240, v252, v253
	v_cvt_pk_bf16_f32 v241, v250, v251
	v_cvt_pk_bf16_f32 v242, v230, v231
	v_cvt_pk_bf16_f32 v243, v232, v233
	v_cvt_pk_bf16_f32 v244, v234, v235
	v_cvt_pk_bf16_f32 v245, v236, v237
	global_store_dwordx4 v[172:173], v[238:241], off
	global_store_dwordx4 v[172:173], v[242:245], off offset:128
	v_lshl_add_u64 v[172:173], v[172:173], 0, s[18:19]
	global_load_dwordx4 v[230:233], v[132:133], off
	global_load_dwordx4 v[234:237], v[132:133], off offset:16
	global_load_dwordx4 v[238:241], v[134:135], off
	global_load_dwordx4 v[242:245], v[134:135], off offset:16
	v_lshl_add_u64 v[132:133], v[132:133], 0, s[18:19]
	v_lshl_add_u64 v[134:135], v[134:135], 0, s[18:19]
	s_waitcnt vmcnt(12)
	v_pk_mul_f32 v[246:247], v[70:71], v[206:207]
	v_pk_mul_f32 v[248:249], v[68:69], v[204:205]
	v_pk_mul_f32 v[250:251], v[66:67], v[210:211]
	v_pk_mul_f32 v[252:253], v[64:65], v[208:209]
	v_pk_mul_f32 v[206:207], v[78:79], v[206:207]
	v_pk_mul_f32 v[204:205], v[76:77], v[204:205]
	v_pk_mul_f32 v[210:211], v[74:75], v[210:211]
	v_pk_mul_f32 v[208:209], v[72:73], v[208:209]
	v_pk_fma_f32 v[246:247], v[78:79], v[198:199], v[246:247] neg_lo:[0,0,1] neg_hi:[0,0,1]
	v_pk_fma_f32 v[248:249], v[76:77], v[196:197], v[248:249] neg_lo:[0,0,1] neg_hi:[0,0,1]
	v_pk_fma_f32 v[250:251], v[74:75], v[202:203], v[250:251] neg_lo:[0,0,1] neg_hi:[0,0,1]
	v_pk_fma_f32 v[252:253], v[72:73], v[200:201], v[252:253] neg_lo:[0,0,1] neg_hi:[0,0,1]
	v_pk_fma_f32 v[198:199], v[70:71], v[198:199], v[206:207]
	v_pk_fma_f32 v[196:197], v[68:69], v[196:197], v[204:205]
	v_pk_fma_f32 v[202:203], v[66:67], v[202:203], v[210:211]
	v_pk_fma_f32 v[200:201], v[64:65], v[200:201], v[208:209]
	v_pk_mul_f32 v[246:247], v[246:247], s[26:27] op_sel_hi:[1,0]
	v_pk_mul_f32 v[248:249], v[248:249], s[26:27] op_sel_hi:[1,0]
	v_pk_mul_f32 v[250:251], v[250:251], s[26:27] op_sel_hi:[1,0]
	v_pk_mul_f32 v[252:253], v[252:253], s[26:27] op_sel_hi:[1,0]
	v_pk_mul_f32 v[198:199], v[198:199], s[26:27] op_sel_hi:[1,0]
	v_pk_mul_f32 v[196:197], v[196:197], s[26:27] op_sel_hi:[1,0]
	v_pk_mul_f32 v[202:203], v[202:203], s[26:27] op_sel_hi:[1,0]
	v_pk_mul_f32 v[200:201], v[200:201], s[26:27] op_sel_hi:[1,0]
	v_cvt_pk_bf16_f32 v204, v248, v249
	v_cvt_pk_bf16_f32 v205, v246, v247
	v_cvt_pk_bf16_f32 v206, v252, v253
	v_cvt_pk_bf16_f32 v207, v250, v251
	v_cvt_pk_bf16_f32 v208, v196, v197
	v_cvt_pk_bf16_f32 v209, v198, v199
	v_cvt_pk_bf16_f32 v210, v200, v201
	v_cvt_pk_bf16_f32 v211, v202, v203
	global_store_dwordx4 v[172:173], v[204:207], off
	global_store_dwordx4 v[172:173], v[208:211], off offset:128
	v_lshl_add_u64 v[172:173], v[172:173], 0, s[24:25]
	global_load_dwordx4 v[196:199], v[132:133], off
	global_load_dwordx4 v[200:203], v[132:133], off offset:16
	global_load_dwordx4 v[204:207], v[134:135], off
	global_load_dwordx4 v[208:211], v[134:135], off offset:16
	v_lshl_add_u64 v[132:133], v[132:133], 0, s[18:19]
	v_lshl_add_u64 v[134:135], v[134:135], 0, s[18:19]
	s_waitcnt vmcnt(12)
	v_pk_mul_f32 v[246:247], v[54:55], v[224:225]
	v_pk_mul_f32 v[248:249], v[52:53], v[222:223]
	v_pk_mul_f32 v[250:251], v[50:51], v[228:229]
	v_pk_mul_f32 v[252:253], v[48:49], v[226:227]
	v_pk_mul_f32 v[224:225], v[62:63], v[224:225]
	v_pk_mul_f32 v[222:223], v[60:61], v[222:223]
	v_pk_mul_f32 v[228:229], v[58:59], v[228:229]
	v_pk_mul_f32 v[226:227], v[56:57], v[226:227]
	v_pk_fma_f32 v[246:247], v[62:63], v[216:217], v[246:247] neg_lo:[0,0,1] neg_hi:[0,0,1]
	v_pk_fma_f32 v[248:249], v[60:61], v[214:215], v[248:249] neg_lo:[0,0,1] neg_hi:[0,0,1]
	v_pk_fma_f32 v[250:251], v[58:59], v[220:221], v[250:251] neg_lo:[0,0,1] neg_hi:[0,0,1]
	v_pk_fma_f32 v[252:253], v[56:57], v[218:219], v[252:253] neg_lo:[0,0,1] neg_hi:[0,0,1]
	v_pk_fma_f32 v[216:217], v[54:55], v[216:217], v[224:225]
	v_pk_fma_f32 v[214:215], v[52:53], v[214:215], v[222:223]
	v_pk_fma_f32 v[220:221], v[50:51], v[220:221], v[228:229]
	v_pk_fma_f32 v[218:219], v[48:49], v[218:219], v[226:227]
	v_pk_mul_f32 v[246:247], v[246:247], s[26:27] op_sel_hi:[1,0]
	v_pk_mul_f32 v[248:249], v[248:249], s[26:27] op_sel_hi:[1,0]
	v_pk_mul_f32 v[250:251], v[250:251], s[26:27] op_sel_hi:[1,0]
	v_pk_mul_f32 v[252:253], v[252:253], s[26:27] op_sel_hi:[1,0]
	v_pk_mul_f32 v[216:217], v[216:217], s[26:27] op_sel_hi:[1,0]
	v_pk_mul_f32 v[214:215], v[214:215], s[26:27] op_sel_hi:[1,0]
	v_pk_mul_f32 v[220:221], v[220:221], s[26:27] op_sel_hi:[1,0]
	v_pk_mul_f32 v[218:219], v[218:219], s[26:27] op_sel_hi:[1,0]
	v_cvt_pk_bf16_f32 v222, v248, v249
	v_cvt_pk_bf16_f32 v223, v246, v247
	v_cvt_pk_bf16_f32 v224, v252, v253
	v_cvt_pk_bf16_f32 v225, v250, v251
	v_cvt_pk_bf16_f32 v226, v214, v215
	v_cvt_pk_bf16_f32 v227, v216, v217
	v_cvt_pk_bf16_f32 v228, v218, v219
	v_cvt_pk_bf16_f32 v229, v220, v221
	global_store_dwordx4 v[172:173], v[222:225], off
	global_store_dwordx4 v[172:173], v[226:229], off offset:128
	v_lshl_add_u64 v[172:173], v[172:173], 0, s[18:19]
	global_load_dwordx4 v[214:217], v[132:133], off
	global_load_dwordx4 v[218:221], v[132:133], off offset:16
	global_load_dwordx4 v[222:225], v[134:135], off
	global_load_dwordx4 v[226:229], v[134:135], off offset:16
	s_waitcnt vmcnt(12)
	v_pk_mul_f32 v[246:247], v[38:39], v[240:241]
	v_pk_mul_f32 v[248:249], v[36:37], v[238:239]
	v_pk_mul_f32 v[250:251], v[34:35], v[244:245]
	v_pk_mul_f32 v[252:253], v[32:33], v[242:243]
	v_pk_mul_f32 v[240:241], v[46:47], v[240:241]
	v_pk_mul_f32 v[238:239], v[44:45], v[238:239]
	v_pk_mul_f32 v[244:245], v[42:43], v[244:245]
	v_pk_mul_f32 v[242:243], v[40:41], v[242:243]
	v_pk_fma_f32 v[246:247], v[46:47], v[232:233], v[246:247] neg_lo:[0,0,1] neg_hi:[0,0,1]
	v_pk_fma_f32 v[248:249], v[44:45], v[230:231], v[248:249] neg_lo:[0,0,1] neg_hi:[0,0,1]
	v_pk_fma_f32 v[250:251], v[42:43], v[236:237], v[250:251] neg_lo:[0,0,1] neg_hi:[0,0,1]
	v_pk_fma_f32 v[252:253], v[40:41], v[234:235], v[252:253] neg_lo:[0,0,1] neg_hi:[0,0,1]
	v_pk_fma_f32 v[232:233], v[38:39], v[232:233], v[240:241]
	v_pk_fma_f32 v[230:231], v[36:37], v[230:231], v[238:239]
	v_pk_fma_f32 v[236:237], v[34:35], v[236:237], v[244:245]
	v_pk_fma_f32 v[234:235], v[32:33], v[234:235], v[242:243]
	v_pk_mul_f32 v[246:247], v[246:247], s[26:27] op_sel_hi:[1,0]
	v_pk_mul_f32 v[248:249], v[248:249], s[26:27] op_sel_hi:[1,0]
	v_pk_mul_f32 v[250:251], v[250:251], s[26:27] op_sel_hi:[1,0]
	v_pk_mul_f32 v[252:253], v[252:253], s[26:27] op_sel_hi:[1,0]
	v_pk_mul_f32 v[232:233], v[232:233], s[26:27] op_sel_hi:[1,0]
	v_pk_mul_f32 v[230:231], v[230:231], s[26:27] op_sel_hi:[1,0]
	v_pk_mul_f32 v[236:237], v[236:237], s[26:27] op_sel_hi:[1,0]
	v_pk_mul_f32 v[234:235], v[234:235], s[26:27] op_sel_hi:[1,0]
	v_cvt_pk_bf16_f32 v238, v248, v249
	v_cvt_pk_bf16_f32 v239, v246, v247
	v_cvt_pk_bf16_f32 v240, v252, v253
	v_cvt_pk_bf16_f32 v241, v250, v251
	v_cvt_pk_bf16_f32 v242, v230, v231
	v_cvt_pk_bf16_f32 v243, v232, v233
	v_cvt_pk_bf16_f32 v244, v234, v235
	v_cvt_pk_bf16_f32 v245, v236, v237
	global_store_dwordx4 v[172:173], v[238:241], off
	global_store_dwordx4 v[172:173], v[242:245], off offset:128
	v_lshl_add_u64 v[172:173], v[172:173], 0, s[18:19]
	s_waitcnt vmcnt(8)
	v_pk_mul_f32 v[246:247], v[22:23], v[206:207]
	v_pk_mul_f32 v[248:249], v[20:21], v[204:205]
	v_pk_mul_f32 v[250:251], v[18:19], v[210:211]
	v_pk_mul_f32 v[252:253], v[16:17], v[208:209]
	v_pk_mul_f32 v[206:207], v[30:31], v[206:207]
	v_pk_mul_f32 v[204:205], v[28:29], v[204:205]
	v_pk_mul_f32 v[210:211], v[26:27], v[210:211]
	v_pk_mul_f32 v[208:209], v[24:25], v[208:209]
	v_pk_fma_f32 v[246:247], v[30:31], v[198:199], v[246:247] neg_lo:[0,0,1] neg_hi:[0,0,1]
	v_pk_fma_f32 v[248:249], v[28:29], v[196:197], v[248:249] neg_lo:[0,0,1] neg_hi:[0,0,1]
	v_pk_fma_f32 v[250:251], v[26:27], v[202:203], v[250:251] neg_lo:[0,0,1] neg_hi:[0,0,1]
	v_pk_fma_f32 v[252:253], v[24:25], v[200:201], v[252:253] neg_lo:[0,0,1] neg_hi:[0,0,1]
	v_pk_fma_f32 v[198:199], v[22:23], v[198:199], v[206:207]
	v_pk_fma_f32 v[196:197], v[20:21], v[196:197], v[204:205]
	v_pk_fma_f32 v[202:203], v[18:19], v[202:203], v[210:211]
	v_pk_fma_f32 v[200:201], v[16:17], v[200:201], v[208:209]
	v_pk_mul_f32 v[246:247], v[246:247], s[26:27] op_sel_hi:[1,0]
	v_pk_mul_f32 v[248:249], v[248:249], s[26:27] op_sel_hi:[1,0]
	v_pk_mul_f32 v[250:251], v[250:251], s[26:27] op_sel_hi:[1,0]
	v_pk_mul_f32 v[252:253], v[252:253], s[26:27] op_sel_hi:[1,0]
	v_pk_mul_f32 v[198:199], v[198:199], s[26:27] op_sel_hi:[1,0]
	v_pk_mul_f32 v[196:197], v[196:197], s[26:27] op_sel_hi:[1,0]
	v_pk_mul_f32 v[202:203], v[202:203], s[26:27] op_sel_hi:[1,0]
	v_pk_mul_f32 v[200:201], v[200:201], s[26:27] op_sel_hi:[1,0]
	v_cvt_pk_bf16_f32 v204, v248, v249
	v_cvt_pk_bf16_f32 v205, v246, v247
	v_cvt_pk_bf16_f32 v206, v252, v253
	v_cvt_pk_bf16_f32 v207, v250, v251
	v_cvt_pk_bf16_f32 v208, v196, v197
	v_cvt_pk_bf16_f32 v209, v198, v199
	v_cvt_pk_bf16_f32 v210, v200, v201
	v_cvt_pk_bf16_f32 v211, v202, v203
	global_store_dwordx4 v[172:173], v[204:207], off
	global_store_dwordx4 v[172:173], v[208:211], off offset:128
	v_lshl_add_u64 v[172:173], v[172:173], 0, s[18:19]
	s_waitcnt vmcnt(4)
	v_pk_mul_f32 v[246:247], v[6:7], v[224:225]
	v_pk_mul_f32 v[248:249], v[4:5], v[222:223]
	v_pk_mul_f32 v[250:251], v[2:3], v[228:229]
	v_pk_mul_f32 v[252:253], v[0:1], v[226:227]
	v_pk_mul_f32 v[224:225], v[14:15], v[224:225]
	v_pk_mul_f32 v[222:223], v[12:13], v[222:223]
	v_pk_mul_f32 v[228:229], v[10:11], v[228:229]
	v_pk_mul_f32 v[226:227], v[8:9], v[226:227]
	v_pk_fma_f32 v[246:247], v[14:15], v[216:217], v[246:247] neg_lo:[0,0,1] neg_hi:[0,0,1]
	v_pk_fma_f32 v[248:249], v[12:13], v[214:215], v[248:249] neg_lo:[0,0,1] neg_hi:[0,0,1]
	v_pk_fma_f32 v[250:251], v[10:11], v[220:221], v[250:251] neg_lo:[0,0,1] neg_hi:[0,0,1]
	v_pk_fma_f32 v[252:253], v[8:9], v[218:219], v[252:253] neg_lo:[0,0,1] neg_hi:[0,0,1]
	v_pk_fma_f32 v[216:217], v[6:7], v[216:217], v[224:225]
	v_pk_fma_f32 v[214:215], v[4:5], v[214:215], v[222:223]
	v_pk_fma_f32 v[220:221], v[2:3], v[220:221], v[228:229]
	v_pk_fma_f32 v[218:219], v[0:1], v[218:219], v[226:227]
	v_pk_mul_f32 v[246:247], v[246:247], s[26:27] op_sel_hi:[1,0]
	v_pk_mul_f32 v[248:249], v[248:249], s[26:27] op_sel_hi:[1,0]
	v_pk_mul_f32 v[250:251], v[250:251], s[26:27] op_sel_hi:[1,0]
	v_pk_mul_f32 v[252:253], v[252:253], s[26:27] op_sel_hi:[1,0]
	v_pk_mul_f32 v[216:217], v[216:217], s[26:27] op_sel_hi:[1,0]
	v_pk_mul_f32 v[214:215], v[214:215], s[26:27] op_sel_hi:[1,0]
	v_pk_mul_f32 v[220:221], v[220:221], s[26:27] op_sel_hi:[1,0]
	v_pk_mul_f32 v[218:219], v[218:219], s[26:27] op_sel_hi:[1,0]
	v_cvt_pk_bf16_f32 v222, v248, v249
	v_cvt_pk_bf16_f32 v223, v246, v247
	v_cvt_pk_bf16_f32 v224, v252, v253
	v_cvt_pk_bf16_f32 v225, v250, v251
	v_cvt_pk_bf16_f32 v226, v214, v215
	v_cvt_pk_bf16_f32 v227, v216, v217
	v_cvt_pk_bf16_f32 v228, v218, v219
	v_cvt_pk_bf16_f32 v229, v220, v221
	global_store_dwordx4 v[172:173], v[222:225], off
	global_store_dwordx4 v[172:173], v[226:229], off offset:128

.LBB0_547:
	s_and_b64 vcc, exec, s[4:5]
	s_cbranch_vccz .LBB0_546
	v_add_u32_e32 v128, s30, v146
	v_ashrrev_i32_e32 v129, 31, v128
	v_lshlrev_b64 v[128:129], 7, v[128:129]
	v_lshl_add_u64 v[134:135], v[158:159], 0, v[128:129]
	v_lshl_add_u64 v[174:175], v[156:157], 0, v[128:129]
	s_and_b32 s4, s28, 0xffffffe0
	s_lshl_b32 s5, s26, 2
	s_lshl_b32 s0, s21, 2
	v_add_u32_e32 v144, s19, v146
	s_add_i32 s19, s4, s5
	s_cmp_eq_u32 s26, 8
	s_cselect_b64 s[4:5], -1, 0
	v_cndmask_b32_e64 v128, v176, 1.0, s[4:5]
	s_and_b64 s[4:5], s[4:5], exec
	s_cselect_b32 s0, s0, s19
	s_cselect_b32 s19, s54, s88
	s_cselect_b32 s21, s53, s96
	s_or_b32 s4, s0, s43
	s_ashr_i32 s5, s4, 31
	s_lshl_b64 s[4:5], s[4:5], 20
	s_add_u32 s4, s21, s4
	v_lshlrev_b64 v[186:187], 7, v[144:145]
	s_addc_u32 s5, s19, s5
	v_mov_b32_e32 v169, v145
	v_lshl_add_u64 v[186:187], s[4:5], 0, v[186:187]
	v_lshl_add_u64 v[186:187], v[186:187], 0, v[168:169]
	v_lshl_add_u64 v[188:189], v[186:187], 0, s[12:13]
	global_load_dwordx4 v[196:199], v[174:175], off
	global_load_dwordx4 v[200:203], v[174:175], off offset:16
	global_load_dwordx4 v[204:207], v[134:135], off
	global_load_dwordx4 v[208:211], v[134:135], off offset:16
	v_lshl_add_u64 v[174:175], v[174:175], 0, s[12:13]
	v_lshl_add_u64 v[134:135], v[134:135], 0, s[12:13]
	global_load_dwordx4 v[214:217], v[174:175], off
	global_load_dwordx4 v[218:221], v[174:175], off offset:16
	global_load_dwordx4 v[222:225], v[134:135], off
	global_load_dwordx4 v[226:229], v[134:135], off offset:16
	v_lshl_add_u64 v[174:175], v[174:175], 0, s[12:13]
	v_lshl_add_u64 v[134:135], v[134:135], 0, s[12:13]
	global_load_dwordx4 v[230:233], v[174:175], off
	global_load_dwordx4 v[234:237], v[174:175], off offset:16
	global_load_dwordx4 v[238:241], v[134:135], off
	global_load_dwordx4 v[242:245], v[134:135], off offset:16
	v_lshl_add_u64 v[174:175], v[174:175], 0, s[12:13]
	v_lshl_add_u64 v[134:135], v[134:135], 0, s[12:13]
	s_waitcnt vmcnt(8)
	v_pk_mul_f32 v[246:247], v[118:119], v[206:207]
	v_pk_mul_f32 v[248:249], v[116:117], v[204:205]
	v_pk_mul_f32 v[250:251], v[114:115], v[210:211]
	v_pk_mul_f32 v[252:253], v[112:113], v[208:209]
	v_pk_mul_f32 v[206:207], v[126:127], v[206:207]
	v_pk_mul_f32 v[204:205], v[124:125], v[204:205]
	v_pk_mul_f32 v[210:211], v[122:123], v[210:211]
	v_pk_mul_f32 v[208:209], v[120:121], v[208:209]
	v_pk_fma_f32 v[246:247], v[126:127], v[198:199], v[246:247] neg_lo:[0,0,1] neg_hi:[0,0,1]
	v_pk_fma_f32 v[248:249], v[124:125], v[196:197], v[248:249] neg_lo:[0,0,1] neg_hi:[0,0,1]
	v_pk_fma_f32 v[250:251], v[122:123], v[202:203], v[250:251] neg_lo:[0,0,1] neg_hi:[0,0,1]
	v_pk_fma_f32 v[252:253], v[120:121], v[200:201], v[252:253] neg_lo:[0,0,1] neg_hi:[0,0,1]
	v_pk_fma_f32 v[198:199], v[118:119], v[198:199], v[206:207]
	v_pk_fma_f32 v[196:197], v[116:117], v[196:197], v[204:205]
	v_pk_fma_f32 v[202:203], v[114:115], v[202:203], v[210:211]
	v_pk_fma_f32 v[200:201], v[112:113], v[200:201], v[208:209]
	v_pk_mul_f32 v[246:247], v[128:129], v[246:247] op_sel_hi:[0,1]
	v_pk_mul_f32 v[248:249], v[128:129], v[248:249] op_sel_hi:[0,1]
	v_pk_mul_f32 v[250:251], v[128:129], v[250:251] op_sel_hi:[0,1]
	v_pk_mul_f32 v[252:253], v[128:129], v[252:253] op_sel_hi:[0,1]
	v_pk_mul_f32 v[198:199], v[128:129], v[198:199] op_sel_hi:[0,1]
	v_pk_mul_f32 v[196:197], v[128:129], v[196:197] op_sel_hi:[0,1]
	v_pk_mul_f32 v[202:203], v[128:129], v[202:203] op_sel_hi:[0,1]
	v_pk_mul_f32 v[200:201], v[128:129], v[200:201] op_sel_hi:[0,1]
	v_cvt_pk_bf16_f32 v204, v248, v249
	v_cvt_pk_bf16_f32 v205, v246, v247
	v_cvt_pk_bf16_f32 v206, v252, v253
	v_cvt_pk_bf16_f32 v207, v250, v251
	v_cvt_pk_bf16_f32 v208, v196, v197
	v_cvt_pk_bf16_f32 v209, v198, v199
	v_cvt_pk_bf16_f32 v210, v200, v201
	v_cvt_pk_bf16_f32 v211, v202, v203
	global_store_dwordx4 v[186:187], v[204:207], off
	global_store_dwordx4 v[186:187], v[208:211], off offset:64
	v_lshl_add_u64 v[186:187], v[186:187], 0, s[12:13]
	global_load_dwordx4 v[196:199], v[174:175], off
	global_load_dwordx4 v[200:203], v[174:175], off offset:16
	global_load_dwordx4 v[204:207], v[134:135], off
	global_load_dwordx4 v[208:211], v[134:135], off offset:16
	v_lshl_add_u64 v[174:175], v[174:175], 0, s[14:15]
	v_lshl_add_u64 v[134:135], v[134:135], 0, s[14:15]
	s_waitcnt vmcnt(10)
	v_pk_mul_f32 v[246:247], v[102:103], v[224:225]
	v_pk_mul_f32 v[248:249], v[100:101], v[222:223]
	v_pk_mul_f32 v[250:251], v[98:99], v[228:229]
	v_pk_mul_f32 v[252:253], v[96:97], v[226:227]
	v_pk_mul_f32 v[224:225], v[110:111], v[224:225]
	v_pk_mul_f32 v[222:223], v[108:109], v[222:223]
	v_pk_mul_f32 v[228:229], v[106:107], v[228:229]
	v_pk_mul_f32 v[226:227], v[104:105], v[226:227]
	v_pk_fma_f32 v[246:247], v[110:111], v[216:217], v[246:247] neg_lo:[0,0,1] neg_hi:[0,0,1]
	v_pk_fma_f32 v[248:249], v[108:109], v[214:215], v[248:249] neg_lo:[0,0,1] neg_hi:[0,0,1]
	v_pk_fma_f32 v[250:251], v[106:107], v[220:221], v[250:251] neg_lo:[0,0,1] neg_hi:[0,0,1]
	v_pk_fma_f32 v[252:253], v[104:105], v[218:219], v[252:253] neg_lo:[0,0,1] neg_hi:[0,0,1]
	v_pk_fma_f32 v[216:217], v[102:103], v[216:217], v[224:225]
	v_pk_fma_f32 v[214:215], v[100:101], v[214:215], v[222:223]
	v_pk_fma_f32 v[220:221], v[98:99], v[220:221], v[228:229]
	v_pk_fma_f32 v[218:219], v[96:97], v[218:219], v[226:227]
	v_pk_mul_f32 v[246:247], v[128:129], v[246:247] op_sel_hi:[0,1]
	v_pk_mul_f32 v[248:249], v[128:129], v[248:249] op_sel_hi:[0,1]
	v_pk_mul_f32 v[250:251], v[128:129], v[250:251] op_sel_hi:[0,1]
	v_pk_mul_f32 v[252:253], v[128:129], v[252:253] op_sel_hi:[0,1]
	v_pk_mul_f32 v[216:217], v[128:129], v[216:217] op_sel_hi:[0,1]
	v_pk_mul_f32 v[214:215], v[128:129], v[214:215] op_sel_hi:[0,1]
	v_pk_mul_f32 v[220:221], v[128:129], v[220:221] op_sel_hi:[0,1]
	v_pk_mul_f32 v[218:219], v[128:129], v[218:219] op_sel_hi:[0,1]
	v_cvt_pk_bf16_f32 v222, v248, v249
	v_cvt_pk_bf16_f32 v223, v246, v247
	v_cvt_pk_bf16_f32 v224, v252, v253
	v_cvt_pk_bf16_f32 v225, v250, v251
	v_cvt_pk_bf16_f32 v226, v214, v215
	v_cvt_pk_bf16_f32 v227, v216, v217
	v_cvt_pk_bf16_f32 v228, v218, v219
	v_cvt_pk_bf16_f32 v229, v220, v221
	global_store_dwordx4 v[186:187], v[222:225], off
	global_store_dwordx4 v[186:187], v[226:229], off offset:64
	v_lshl_add_u64 v[186:187], v[186:187], 0, s[12:13]
	global_load_dwordx4 v[214:217], v[174:175], off
	global_load_dwordx4 v[218:221], v[174:175], off offset:16
	global_load_dwordx4 v[222:225], v[134:135], off
	global_load_dwordx4 v[226:229], v[134:135], off offset:16
	v_lshl_add_u64 v[174:175], v[174:175], 0, s[12:13]
	v_lshl_add_u64 v[134:135], v[134:135], 0, s[12:13]
	s_waitcnt vmcnt(12)
	v_pk_mul_f32 v[246:247], v[86:87], v[240:241]
	v_pk_mul_f32 v[248:249], v[84:85], v[238:239]
	v_pk_mul_f32 v[250:251], v[82:83], v[244:245]
	v_pk_mul_f32 v[252:253], v[80:81], v[242:243]
	v_pk_mul_f32 v[240:241], v[94:95], v[240:241]
	v_pk_mul_f32 v[238:239], v[92:93], v[238:239]
	v_pk_mul_f32 v[244:245], v[90:91], v[244:245]
	v_pk_mul_f32 v[242:243], v[88:89], v[242:243]
	v_pk_fma_f32 v[246:247], v[94:95], v[232:233], v[246:247] neg_lo:[0,0,1] neg_hi:[0,0,1]
	v_pk_fma_f32 v[248:249], v[92:93], v[230:231], v[248:249] neg_lo:[0,0,1] neg_hi:[0,0,1]
	v_pk_fma_f32 v[250:251], v[90:91], v[236:237], v[250:251] neg_lo:[0,0,1] neg_hi:[0,0,1]
	v_pk_fma_f32 v[252:253], v[88:89], v[234:235], v[252:253] neg_lo:[0,0,1] neg_hi:[0,0,1]
	v_pk_fma_f32 v[232:233], v[86:87], v[232:233], v[240:241]
	v_pk_fma_f32 v[230:231], v[84:85], v[230:231], v[238:239]
	v_pk_fma_f32 v[236:237], v[82:83], v[236:237], v[244:245]
	v_pk_fma_f32 v[234:235], v[80:81], v[234:235], v[242:243]
	v_pk_mul_f32 v[246:247], v[128:129], v[246:247] op_sel_hi:[0,1]
	v_pk_mul_f32 v[248:249], v[128:129], v[248:249] op_sel_hi:[0,1]
	v_pk_mul_f32 v[250:251], v[128:129], v[250:251] op_sel_hi:[0,1]
	v_pk_mul_f32 v[252:253], v[128:129], v[252:253] op_sel_hi:[0,1]
	v_pk_mul_f32 v[232:233], v[128:129], v[232:233] op_sel_hi:[0,1]
	v_pk_mul_f32 v[230:231], v[128:129], v[230:231] op_sel_hi:[0,1]
	v_pk_mul_f32 v[236:237], v[128:129], v[236:237] op_sel_hi:[0,1]
	v_pk_mul_f32 v[234:235], v[128:129], v[234:235] op_sel_hi:[0,1]
	v_cvt_pk_bf16_f32 v238, v248, v249
	v_cvt_pk_bf16_f32 v239, v246, v247
	v_cvt_pk_bf16_f32 v240, v252, v253
	v_cvt_pk_bf16_f32 v241, v250, v251
	v_cvt_pk_bf16_f32 v242, v230, v231
	v_cvt_pk_bf16_f32 v243, v232, v233
	v_cvt_pk_bf16_f32 v244, v234, v235
	v_cvt_pk_bf16_f32 v245, v236, v237
	global_store_dwordx4 v[186:187], v[238:241], off
	global_store_dwordx4 v[186:187], v[242:245], off offset:64
	v_lshl_add_u64 v[186:187], v[186:187], 0, s[12:13]
	global_load_dwordx4 v[230:233], v[174:175], off
	global_load_dwordx4 v[234:237], v[174:175], off offset:16
	global_load_dwordx4 v[238:241], v[134:135], off
	global_load_dwordx4 v[242:245], v[134:135], off offset:16
	v_lshl_add_u64 v[174:175], v[174:175], 0, s[12:13]
	v_lshl_add_u64 v[134:135], v[134:135], 0, s[12:13]
	s_waitcnt vmcnt(12)
	v_pk_mul_f32 v[246:247], v[70:71], v[206:207]
	v_pk_mul_f32 v[248:249], v[68:69], v[204:205]
	v_pk_mul_f32 v[250:251], v[66:67], v[210:211]
	v_pk_mul_f32 v[252:253], v[64:65], v[208:209]
	v_pk_mul_f32 v[206:207], v[78:79], v[206:207]
	v_pk_mul_f32 v[204:205], v[76:77], v[204:205]
	v_pk_mul_f32 v[210:211], v[74:75], v[210:211]
	v_pk_mul_f32 v[208:209], v[72:73], v[208:209]
	v_pk_fma_f32 v[246:247], v[78:79], v[198:199], v[246:247] neg_lo:[0,0,1] neg_hi:[0,0,1]
	v_pk_fma_f32 v[248:249], v[76:77], v[196:197], v[248:249] neg_lo:[0,0,1] neg_hi:[0,0,1]
	v_pk_fma_f32 v[250:251], v[74:75], v[202:203], v[250:251] neg_lo:[0,0,1] neg_hi:[0,0,1]
	v_pk_fma_f32 v[252:253], v[72:73], v[200:201], v[252:253] neg_lo:[0,0,1] neg_hi:[0,0,1]
	v_pk_fma_f32 v[198:199], v[70:71], v[198:199], v[206:207]
	v_pk_fma_f32 v[196:197], v[68:69], v[196:197], v[204:205]
	v_pk_fma_f32 v[202:203], v[66:67], v[202:203], v[210:211]
	v_pk_fma_f32 v[200:201], v[64:65], v[200:201], v[208:209]
	v_pk_mul_f32 v[246:247], v[128:129], v[246:247] op_sel_hi:[0,1]
	v_pk_mul_f32 v[248:249], v[128:129], v[248:249] op_sel_hi:[0,1]
	v_pk_mul_f32 v[250:251], v[128:129], v[250:251] op_sel_hi:[0,1]
	v_pk_mul_f32 v[252:253], v[128:129], v[252:253] op_sel_hi:[0,1]
	v_pk_mul_f32 v[198:199], v[128:129], v[198:199] op_sel_hi:[0,1]
	v_pk_mul_f32 v[196:197], v[128:129], v[196:197] op_sel_hi:[0,1]
	v_pk_mul_f32 v[202:203], v[128:129], v[202:203] op_sel_hi:[0,1]
	v_pk_mul_f32 v[200:201], v[128:129], v[200:201] op_sel_hi:[0,1]
	v_cvt_pk_bf16_f32 v204, v248, v249
	v_cvt_pk_bf16_f32 v205, v246, v247
	v_cvt_pk_bf16_f32 v206, v252, v253
	v_cvt_pk_bf16_f32 v207, v250, v251
	v_cvt_pk_bf16_f32 v208, v196, v197
	v_cvt_pk_bf16_f32 v209, v198, v199
	v_cvt_pk_bf16_f32 v210, v200, v201
	v_cvt_pk_bf16_f32 v211, v202, v203
	global_store_dwordx4 v[186:187], v[204:207], off
	global_store_dwordx4 v[186:187], v[208:211], off offset:64
	v_lshl_add_u64 v[186:187], v[186:187], 0, s[14:15]
	global_load_dwordx4 v[196:199], v[174:175], off
	global_load_dwordx4 v[200:203], v[174:175], off offset:16
	global_load_dwordx4 v[204:207], v[134:135], off
	global_load_dwordx4 v[208:211], v[134:135], off offset:16
	v_lshl_add_u64 v[174:175], v[174:175], 0, s[12:13]
	v_lshl_add_u64 v[134:135], v[134:135], 0, s[12:13]
	s_waitcnt vmcnt(12)
	v_pk_mul_f32 v[246:247], v[54:55], v[224:225]
	v_pk_mul_f32 v[248:249], v[52:53], v[222:223]
	v_pk_mul_f32 v[250:251], v[50:51], v[228:229]
	v_pk_mul_f32 v[252:253], v[48:49], v[226:227]
	v_pk_mul_f32 v[224:225], v[62:63], v[224:225]
	v_pk_mul_f32 v[222:223], v[60:61], v[222:223]
	v_pk_mul_f32 v[228:229], v[58:59], v[228:229]
	v_pk_mul_f32 v[226:227], v[56:57], v[226:227]
	v_pk_fma_f32 v[246:247], v[62:63], v[216:217], v[246:247] neg_lo:[0,0,1] neg_hi:[0,0,1]
	v_pk_fma_f32 v[248:249], v[60:61], v[214:215], v[248:249] neg_lo:[0,0,1] neg_hi:[0,0,1]
	v_pk_fma_f32 v[250:251], v[58:59], v[220:221], v[250:251] neg_lo:[0,0,1] neg_hi:[0,0,1]
	v_pk_fma_f32 v[252:253], v[56:57], v[218:219], v[252:253] neg_lo:[0,0,1] neg_hi:[0,0,1]
	v_pk_fma_f32 v[216:217], v[54:55], v[216:217], v[224:225]
	v_pk_fma_f32 v[214:215], v[52:53], v[214:215], v[222:223]
	v_pk_fma_f32 v[220:221], v[50:51], v[220:221], v[228:229]
	v_pk_fma_f32 v[218:219], v[48:49], v[218:219], v[226:227]
	v_pk_mul_f32 v[246:247], v[128:129], v[246:247] op_sel_hi:[0,1]
	v_pk_mul_f32 v[248:249], v[128:129], v[248:249] op_sel_hi:[0,1]
	v_pk_mul_f32 v[250:251], v[128:129], v[250:251] op_sel_hi:[0,1]
	v_pk_mul_f32 v[252:253], v[128:129], v[252:253] op_sel_hi:[0,1]
	v_pk_mul_f32 v[216:217], v[128:129], v[216:217] op_sel_hi:[0,1]
	v_pk_mul_f32 v[214:215], v[128:129], v[214:215] op_sel_hi:[0,1]
	v_pk_mul_f32 v[220:221], v[128:129], v[220:221] op_sel_hi:[0,1]
	v_pk_mul_f32 v[218:219], v[128:129], v[218:219] op_sel_hi:[0,1]
	v_cvt_pk_bf16_f32 v222, v248, v249
	v_cvt_pk_bf16_f32 v223, v246, v247
	v_cvt_pk_bf16_f32 v224, v252, v253
	v_cvt_pk_bf16_f32 v225, v250, v251
	v_cvt_pk_bf16_f32 v226, v214, v215
	v_cvt_pk_bf16_f32 v227, v216, v217
	v_cvt_pk_bf16_f32 v228, v218, v219
	v_cvt_pk_bf16_f32 v229, v220, v221
	global_store_dwordx4 v[186:187], v[222:225], off
	global_store_dwordx4 v[186:187], v[226:229], off offset:64
	v_lshl_add_u64 v[186:187], v[186:187], 0, s[12:13]
	global_load_dwordx4 v[214:217], v[174:175], off
	global_load_dwordx4 v[218:221], v[174:175], off offset:16
	global_load_dwordx4 v[222:225], v[134:135], off
	global_load_dwordx4 v[226:229], v[134:135], off offset:16
	s_waitcnt vmcnt(12)
	v_pk_mul_f32 v[246:247], v[38:39], v[240:241]
	v_pk_mul_f32 v[248:249], v[36:37], v[238:239]
	v_pk_mul_f32 v[250:251], v[34:35], v[244:245]
	v_pk_mul_f32 v[252:253], v[32:33], v[242:243]
	v_pk_mul_f32 v[240:241], v[46:47], v[240:241]
	v_pk_mul_f32 v[238:239], v[44:45], v[238:239]
	v_pk_mul_f32 v[244:245], v[42:43], v[244:245]
	v_pk_mul_f32 v[242:243], v[40:41], v[242:243]
	v_pk_fma_f32 v[246:247], v[46:47], v[232:233], v[246:247] neg_lo:[0,0,1] neg_hi:[0,0,1]
	v_pk_fma_f32 v[248:249], v[44:45], v[230:231], v[248:249] neg_lo:[0,0,1] neg_hi:[0,0,1]
	v_pk_fma_f32 v[250:251], v[42:43], v[236:237], v[250:251] neg_lo:[0,0,1] neg_hi:[0,0,1]
	v_pk_fma_f32 v[252:253], v[40:41], v[234:235], v[252:253] neg_lo:[0,0,1] neg_hi:[0,0,1]
	v_pk_fma_f32 v[232:233], v[38:39], v[232:233], v[240:241]
	v_pk_fma_f32 v[230:231], v[36:37], v[230:231], v[238:239]
	v_pk_fma_f32 v[236:237], v[34:35], v[236:237], v[244:245]
	v_pk_fma_f32 v[234:235], v[32:33], v[234:235], v[242:243]
	v_pk_mul_f32 v[246:247], v[128:129], v[246:247] op_sel_hi:[0,1]
	v_pk_mul_f32 v[248:249], v[128:129], v[248:249] op_sel_hi:[0,1]
	v_pk_mul_f32 v[250:251], v[128:129], v[250:251] op_sel_hi:[0,1]
	v_pk_mul_f32 v[252:253], v[128:129], v[252:253] op_sel_hi:[0,1]
	v_pk_mul_f32 v[232:233], v[128:129], v[232:233] op_sel_hi:[0,1]
	v_pk_mul_f32 v[230:231], v[128:129], v[230:231] op_sel_hi:[0,1]
	v_pk_mul_f32 v[236:237], v[128:129], v[236:237] op_sel_hi:[0,1]
	v_pk_mul_f32 v[234:235], v[128:129], v[234:235] op_sel_hi:[0,1]
	v_cvt_pk_bf16_f32 v238, v248, v249
	v_cvt_pk_bf16_f32 v239, v246, v247
	v_cvt_pk_bf16_f32 v240, v252, v253
	v_cvt_pk_bf16_f32 v241, v250, v251
	v_cvt_pk_bf16_f32 v242, v230, v231
	v_cvt_pk_bf16_f32 v243, v232, v233
	v_cvt_pk_bf16_f32 v244, v234, v235
	v_cvt_pk_bf16_f32 v245, v236, v237
	global_store_dwordx4 v[186:187], v[238:241], off
	global_store_dwordx4 v[186:187], v[242:245], off offset:64
	v_lshl_add_u64 v[186:187], v[186:187], 0, s[12:13]
	s_waitcnt vmcnt(8)
	v_pk_mul_f32 v[246:247], v[22:23], v[206:207]
	v_pk_mul_f32 v[248:249], v[20:21], v[204:205]
	v_pk_mul_f32 v[250:251], v[18:19], v[210:211]
	v_pk_mul_f32 v[252:253], v[16:17], v[208:209]
	v_pk_mul_f32 v[206:207], v[30:31], v[206:207]
	v_pk_mul_f32 v[204:205], v[28:29], v[204:205]
	v_pk_mul_f32 v[210:211], v[26:27], v[210:211]
	v_pk_mul_f32 v[208:209], v[24:25], v[208:209]
	v_pk_fma_f32 v[246:247], v[30:31], v[198:199], v[246:247] neg_lo:[0,0,1] neg_hi:[0,0,1]
	v_pk_fma_f32 v[248:249], v[28:29], v[196:197], v[248:249] neg_lo:[0,0,1] neg_hi:[0,0,1]
	v_pk_fma_f32 v[250:251], v[26:27], v[202:203], v[250:251] neg_lo:[0,0,1] neg_hi:[0,0,1]
	v_pk_fma_f32 v[252:253], v[24:25], v[200:201], v[252:253] neg_lo:[0,0,1] neg_hi:[0,0,1]
	v_pk_fma_f32 v[198:199], v[22:23], v[198:199], v[206:207]
	v_pk_fma_f32 v[196:197], v[20:21], v[196:197], v[204:205]
	v_pk_fma_f32 v[202:203], v[18:19], v[202:203], v[210:211]
	v_pk_fma_f32 v[200:201], v[16:17], v[200:201], v[208:209]
	v_pk_mul_f32 v[246:247], v[128:129], v[246:247] op_sel_hi:[0,1]
	v_pk_mul_f32 v[248:249], v[128:129], v[248:249] op_sel_hi:[0,1]
	v_pk_mul_f32 v[250:251], v[128:129], v[250:251] op_sel_hi:[0,1]
	v_pk_mul_f32 v[252:253], v[128:129], v[252:253] op_sel_hi:[0,1]
	v_pk_mul_f32 v[198:199], v[128:129], v[198:199] op_sel_hi:[0,1]
	v_pk_mul_f32 v[196:197], v[128:129], v[196:197] op_sel_hi:[0,1]
	v_pk_mul_f32 v[202:203], v[128:129], v[202:203] op_sel_hi:[0,1]
	v_pk_mul_f32 v[200:201], v[128:129], v[200:201] op_sel_hi:[0,1]
	v_cvt_pk_bf16_f32 v204, v248, v249
	v_cvt_pk_bf16_f32 v205, v246, v247
	v_cvt_pk_bf16_f32 v206, v252, v253
	v_cvt_pk_bf16_f32 v207, v250, v251
	v_cvt_pk_bf16_f32 v208, v196, v197
	v_cvt_pk_bf16_f32 v209, v198, v199
	v_cvt_pk_bf16_f32 v210, v200, v201
	v_cvt_pk_bf16_f32 v211, v202, v203
	global_store_dwordx4 v[186:187], v[204:207], off
	global_store_dwordx4 v[186:187], v[208:211], off offset:64
	v_lshl_add_u64 v[186:187], v[186:187], 0, s[12:13]
	s_waitcnt vmcnt(4)
	v_pk_mul_f32 v[246:247], v[6:7], v[224:225]
	v_pk_mul_f32 v[248:249], v[4:5], v[222:223]
	v_pk_mul_f32 v[250:251], v[2:3], v[228:229]
	v_pk_mul_f32 v[252:253], v[0:1], v[226:227]
	v_pk_mul_f32 v[224:225], v[14:15], v[224:225]
	v_pk_mul_f32 v[222:223], v[12:13], v[222:223]
	v_pk_mul_f32 v[228:229], v[10:11], v[228:229]
	v_pk_mul_f32 v[226:227], v[8:9], v[226:227]
	v_pk_fma_f32 v[246:247], v[14:15], v[216:217], v[246:247] neg_lo:[0,0,1] neg_hi:[0,0,1]
	v_pk_fma_f32 v[248:249], v[12:13], v[214:215], v[248:249] neg_lo:[0,0,1] neg_hi:[0,0,1]
	v_pk_fma_f32 v[250:251], v[10:11], v[220:221], v[250:251] neg_lo:[0,0,1] neg_hi:[0,0,1]
	v_pk_fma_f32 v[252:253], v[8:9], v[218:219], v[252:253] neg_lo:[0,0,1] neg_hi:[0,0,1]
	v_pk_fma_f32 v[216:217], v[6:7], v[216:217], v[224:225]
	v_pk_fma_f32 v[214:215], v[4:5], v[214:215], v[222:223]
	v_pk_fma_f32 v[220:221], v[2:3], v[220:221], v[228:229]
	v_pk_fma_f32 v[218:219], v[0:1], v[218:219], v[226:227]
	v_pk_mul_f32 v[246:247], v[128:129], v[246:247] op_sel_hi:[0,1]
	v_pk_mul_f32 v[248:249], v[128:129], v[248:249] op_sel_hi:[0,1]
	v_pk_mul_f32 v[250:251], v[128:129], v[250:251] op_sel_hi:[0,1]
	v_pk_mul_f32 v[252:253], v[128:129], v[252:253] op_sel_hi:[0,1]
	v_pk_mul_f32 v[216:217], v[128:129], v[216:217] op_sel_hi:[0,1]
	v_pk_mul_f32 v[214:215], v[128:129], v[214:215] op_sel_hi:[0,1]
	v_pk_mul_f32 v[220:221], v[128:129], v[220:221] op_sel_hi:[0,1]
	v_pk_mul_f32 v[218:219], v[128:129], v[218:219] op_sel_hi:[0,1]
	v_cvt_pk_bf16_f32 v222, v248, v249
	v_cvt_pk_bf16_f32 v223, v246, v247
	v_cvt_pk_bf16_f32 v224, v252, v253
	v_cvt_pk_bf16_f32 v225, v250, v251
	v_cvt_pk_bf16_f32 v226, v214, v215
	v_cvt_pk_bf16_f32 v227, v216, v217
	v_cvt_pk_bf16_f32 v228, v218, v219
	v_cvt_pk_bf16_f32 v229, v220, v221
	global_store_dwordx4 v[186:187], v[222:225], off
	global_store_dwordx4 v[186:187], v[226:229], off offset:64
	s_andn2_b64 vcc, exec, s[2:3]
	s_mov_b64 s[2:3], -1
	s_cbranch_vccnz .LBB0_501

.LBB0_1521:
	s_and_b64 vcc, exec, s[4:5]
	s_cbranch_vccz .LBB0_1526
	v_add_u32_e32 v128, s38, v146
	v_ashrrev_i32_e32 v129, 31, v128
	v_lshlrev_b64 v[128:129], 8, v[128:129]
	v_lshl_add_u64 v[132:133], v[150:151], 0, v[128:129]
	v_lshl_add_u64 v[134:135], v[152:153], 0, v[128:129]
	s_lshl_b32 s0, s29, 4
	s_lshl_b32 s29, s36, 1
	s_cmp_gt_u32 s36, 7
	s_mov_b64 s[4:5], -1
	v_lshl_add_u64 v[128:129], v[132:133], 0, s[16:17]
	v_lshl_add_u64 v[130:131], v[134:135], 0, s[16:17]
	s_cbranch_scc0 .LBB0_1524
	s_and_b32 s4, s29, 14
	s_or_b32 s4, s0, s4
	s_or_b32 s4, s4, s57
	s_ashr_i32 s5, s4, 31
	s_lshl_b64 s[4:5], s[4:5], 21
	s_add_u32 s4, s67, s4
	s_addc_u32 s5, s68, s5
	s_lshl_b32 s33, s27, 8
	s_add_u32 s4, s4, s33
	s_addc_u32 s5, s5, 0
	s_add_u32 s4, s4, s12
	v_mov_b32_e32 v163, v145
	s_addc_u32 s5, s5, s13
	v_mov_b32_e32 v165, v145
	v_lshl_add_u64 v[190:191], s[4:5], 0, v[162:163]
	v_lshl_add_u64 v[190:191], v[190:191], 0, v[164:165]
	v_add_co_u32_e32 v192, vcc, s71, v190
	v_mov_b64_e32 v[186:187], v[130:131]
	v_mov_b64_e32 v[188:189], v[128:129]
	v_addc_co_u32_e32 v193, vcc, 0, v191, vcc
	v_lshl_add_u64 v[194:195], v[190:191], 0, s[14:15]
	s_mov_b64 s[4:5], 0
	v_add_co_u32_e32 v192, vcc, 0x1000, v190
	s_nop 1
	v_addc_co_u32_e32 v193, vcc, 0, v191, vcc
	global_load_dwordx4 v[196:199], v[132:133], off
	global_load_dwordx4 v[200:203], v[132:133], off offset:16
	global_load_dwordx4 v[204:207], v[134:135], off
	global_load_dwordx4 v[208:211], v[134:135], off offset:16
	v_lshl_add_u64 v[132:133], v[132:133], 0, s[16:17]
	v_lshl_add_u64 v[134:135], v[134:135], 0, s[16:17]
	global_load_dwordx4 v[214:217], v[132:133], off
	global_load_dwordx4 v[218:221], v[132:133], off offset:16
	global_load_dwordx4 v[222:225], v[134:135], off
	global_load_dwordx4 v[226:229], v[134:135], off offset:16
	v_lshl_add_u64 v[132:133], v[132:133], 0, s[16:17]
	v_lshl_add_u64 v[134:135], v[134:135], 0, s[16:17]
	global_load_dwordx4 v[230:233], v[132:133], off
	global_load_dwordx4 v[234:237], v[132:133], off offset:16
	global_load_dwordx4 v[238:241], v[134:135], off
	global_load_dwordx4 v[242:245], v[134:135], off offset:16
	v_lshl_add_u64 v[132:133], v[132:133], 0, s[16:17]
	v_lshl_add_u64 v[134:135], v[134:135], 0, s[16:17]
	s_waitcnt vmcnt(8)
	v_pk_mul_f32 v[246:247], v[118:119], v[206:207]
	v_pk_mul_f32 v[248:249], v[116:117], v[204:205]
	v_pk_mul_f32 v[250:251], v[114:115], v[210:211]
	v_pk_mul_f32 v[252:253], v[112:113], v[208:209]
	v_pk_mul_f32 v[206:207], v[126:127], v[206:207]
	v_pk_mul_f32 v[204:205], v[124:125], v[204:205]
	v_pk_mul_f32 v[210:211], v[122:123], v[210:211]
	v_pk_mul_f32 v[208:209], v[120:121], v[208:209]
	v_pk_fma_f32 v[246:247], v[126:127], v[198:199], v[246:247] neg_lo:[0,0,1] neg_hi:[0,0,1]
	v_pk_fma_f32 v[248:249], v[124:125], v[196:197], v[248:249] neg_lo:[0,0,1] neg_hi:[0,0,1]
	v_pk_fma_f32 v[250:251], v[122:123], v[202:203], v[250:251] neg_lo:[0,0,1] neg_hi:[0,0,1]
	v_pk_fma_f32 v[252:253], v[120:121], v[200:201], v[252:253] neg_lo:[0,0,1] neg_hi:[0,0,1]
	v_pk_fma_f32 v[198:199], v[118:119], v[198:199], v[206:207]
	v_pk_fma_f32 v[196:197], v[116:117], v[196:197], v[204:205]
	v_pk_fma_f32 v[202:203], v[114:115], v[202:203], v[210:211]
	v_pk_fma_f32 v[200:201], v[112:113], v[200:201], v[208:209]
	v_cvt_pk_bf16_f32 v204, v248, v249
	v_cvt_pk_bf16_f32 v205, v246, v247
	v_cvt_pk_bf16_f32 v206, v252, v253
	v_cvt_pk_bf16_f32 v207, v250, v251
	v_cvt_pk_bf16_f32 v208, v196, v197
	v_cvt_pk_bf16_f32 v209, v198, v199
	v_cvt_pk_bf16_f32 v210, v200, v201
	v_cvt_pk_bf16_f32 v211, v202, v203
	global_store_dwordx4 v[190:191], v[204:207], off
	global_store_dwordx4 v[192:193], v[208:211], off
	v_lshl_add_u64 v[190:191], v[190:191], 0, s[14:15]
	v_lshl_add_u64 v[192:193], v[192:193], 0, s[14:15]
	global_load_dwordx4 v[196:199], v[132:133], off
	global_load_dwordx4 v[200:203], v[132:133], off offset:16
	global_load_dwordx4 v[204:207], v[134:135], off
	global_load_dwordx4 v[208:211], v[134:135], off offset:16
	v_lshl_add_u64 v[132:133], v[132:133], 0, s[22:23]
	v_lshl_add_u64 v[134:135], v[134:135], 0, s[22:23]
	s_waitcnt vmcnt(10)
	v_pk_mul_f32 v[246:247], v[102:103], v[224:225]
	v_pk_mul_f32 v[248:249], v[100:101], v[222:223]
	v_pk_mul_f32 v[250:251], v[98:99], v[228:229]
	v_pk_mul_f32 v[252:253], v[96:97], v[226:227]
	v_pk_mul_f32 v[224:225], v[110:111], v[224:225]
	v_pk_mul_f32 v[222:223], v[108:109], v[222:223]
	v_pk_mul_f32 v[228:229], v[106:107], v[228:229]
	v_pk_mul_f32 v[226:227], v[104:105], v[226:227]
	v_pk_fma_f32 v[246:247], v[110:111], v[216:217], v[246:247] neg_lo:[0,0,1] neg_hi:[0,0,1]
	v_pk_fma_f32 v[248:249], v[108:109], v[214:215], v[248:249] neg_lo:[0,0,1] neg_hi:[0,0,1]
	v_pk_fma_f32 v[250:251], v[106:107], v[220:221], v[250:251] neg_lo:[0,0,1] neg_hi:[0,0,1]
	v_pk_fma_f32 v[252:253], v[104:105], v[218:219], v[252:253] neg_lo:[0,0,1] neg_hi:[0,0,1]
	v_pk_fma_f32 v[216:217], v[102:103], v[216:217], v[224:225]
	v_pk_fma_f32 v[214:215], v[100:101], v[214:215], v[222:223]
	v_pk_fma_f32 v[220:221], v[98:99], v[220:221], v[228:229]
	v_pk_fma_f32 v[218:219], v[96:97], v[218:219], v[226:227]
	v_cvt_pk_bf16_f32 v222, v248, v249
	v_cvt_pk_bf16_f32 v223, v246, v247
	v_cvt_pk_bf16_f32 v224, v252, v253
	v_cvt_pk_bf16_f32 v225, v250, v251
	v_cvt_pk_bf16_f32 v226, v214, v215
	v_cvt_pk_bf16_f32 v227, v216, v217
	v_cvt_pk_bf16_f32 v228, v218, v219
	v_cvt_pk_bf16_f32 v229, v220, v221
	global_store_dwordx4 v[190:191], v[222:225], off
	global_store_dwordx4 v[192:193], v[226:229], off
	v_lshl_add_u64 v[190:191], v[190:191], 0, s[18:19]
	v_lshl_add_u64 v[192:193], v[192:193], 0, s[18:19]
	global_load_dwordx4 v[214:217], v[132:133], off
	global_load_dwordx4 v[218:221], v[132:133], off offset:16
	global_load_dwordx4 v[222:225], v[134:135], off
	global_load_dwordx4 v[226:229], v[134:135], off offset:16
	v_lshl_add_u64 v[132:133], v[132:133], 0, s[16:17]
	v_lshl_add_u64 v[134:135], v[134:135], 0, s[16:17]
	s_waitcnt vmcnt(12)
	v_pk_mul_f32 v[246:247], v[86:87], v[240:241]
	v_pk_mul_f32 v[248:249], v[84:85], v[238:239]
	v_pk_mul_f32 v[250:251], v[82:83], v[244:245]
	v_pk_mul_f32 v[252:253], v[80:81], v[242:243]
	v_pk_mul_f32 v[240:241], v[94:95], v[240:241]
	v_pk_mul_f32 v[238:239], v[92:93], v[238:239]
	v_pk_mul_f32 v[244:245], v[90:91], v[244:245]
	v_pk_mul_f32 v[242:243], v[88:89], v[242:243]
	v_pk_fma_f32 v[246:247], v[94:95], v[232:233], v[246:247] neg_lo:[0,0,1] neg_hi:[0,0,1]
	v_pk_fma_f32 v[248:249], v[92:93], v[230:231], v[248:249] neg_lo:[0,0,1] neg_hi:[0,0,1]
	v_pk_fma_f32 v[250:251], v[90:91], v[236:237], v[250:251] neg_lo:[0,0,1] neg_hi:[0,0,1]
	v_pk_fma_f32 v[252:253], v[88:89], v[234:235], v[252:253] neg_lo:[0,0,1] neg_hi:[0,0,1]
	v_pk_fma_f32 v[232:233], v[86:87], v[232:233], v[240:241]
	v_pk_fma_f32 v[230:231], v[84:85], v[230:231], v[238:239]
	v_pk_fma_f32 v[236:237], v[82:83], v[236:237], v[244:245]
	v_pk_fma_f32 v[234:235], v[80:81], v[234:235], v[242:243]
	v_cvt_pk_bf16_f32 v238, v248, v249
	v_cvt_pk_bf16_f32 v239, v246, v247
	v_cvt_pk_bf16_f32 v240, v252, v253
	v_cvt_pk_bf16_f32 v241, v250, v251
	v_cvt_pk_bf16_f32 v242, v230, v231
	v_cvt_pk_bf16_f32 v243, v232, v233
	v_cvt_pk_bf16_f32 v244, v234, v235
	v_cvt_pk_bf16_f32 v245, v236, v237
	global_store_dwordx4 v[190:191], v[238:241], off
	global_store_dwordx4 v[192:193], v[242:245], off
	v_lshl_add_u64 v[190:191], v[190:191], 0, s[14:15]
	v_lshl_add_u64 v[192:193], v[192:193], 0, s[14:15]
	global_load_dwordx4 v[230:233], v[132:133], off
	global_load_dwordx4 v[234:237], v[132:133], off offset:16
	global_load_dwordx4 v[238:241], v[134:135], off
	global_load_dwordx4 v[242:245], v[134:135], off offset:16
	v_lshl_add_u64 v[132:133], v[132:133], 0, s[16:17]
	v_lshl_add_u64 v[134:135], v[134:135], 0, s[16:17]
	s_waitcnt vmcnt(12)
	v_pk_mul_f32 v[246:247], v[70:71], v[206:207]
	v_pk_mul_f32 v[248:249], v[68:69], v[204:205]
	v_pk_mul_f32 v[250:251], v[66:67], v[210:211]
	v_pk_mul_f32 v[252:253], v[64:65], v[208:209]
	v_pk_mul_f32 v[206:207], v[78:79], v[206:207]
	v_pk_mul_f32 v[204:205], v[76:77], v[204:205]
	v_pk_mul_f32 v[210:211], v[74:75], v[210:211]
	v_pk_mul_f32 v[208:209], v[72:73], v[208:209]
	v_pk_fma_f32 v[246:247], v[78:79], v[198:199], v[246:247] neg_lo:[0,0,1] neg_hi:[0,0,1]
	v_pk_fma_f32 v[248:249], v[76:77], v[196:197], v[248:249] neg_lo:[0,0,1] neg_hi:[0,0,1]
	v_pk_fma_f32 v[250:251], v[74:75], v[202:203], v[250:251] neg_lo:[0,0,1] neg_hi:[0,0,1]
	v_pk_fma_f32 v[252:253], v[72:73], v[200:201], v[252:253] neg_lo:[0,0,1] neg_hi:[0,0,1]
	v_pk_fma_f32 v[198:199], v[70:71], v[198:199], v[206:207]
	v_pk_fma_f32 v[196:197], v[68:69], v[196:197], v[204:205]
	v_pk_fma_f32 v[202:203], v[66:67], v[202:203], v[210:211]
	v_pk_fma_f32 v[200:201], v[64:65], v[200:201], v[208:209]
	v_cvt_pk_bf16_f32 v204, v248, v249
	v_cvt_pk_bf16_f32 v205, v246, v247
	v_cvt_pk_bf16_f32 v206, v252, v253
	v_cvt_pk_bf16_f32 v207, v250, v251
	v_cvt_pk_bf16_f32 v208, v196, v197
	v_cvt_pk_bf16_f32 v209, v198, v199
	v_cvt_pk_bf16_f32 v210, v200, v201
	v_cvt_pk_bf16_f32 v211, v202, v203
	global_store_dwordx4 v[190:191], v[204:207], off
	global_store_dwordx4 v[192:193], v[208:211], off
	v_lshl_add_u64 v[190:191], v[190:191], 0, s[20:21]
	v_lshl_add_u64 v[192:193], v[192:193], 0, s[20:21]
	global_load_dwordx4 v[196:199], v[132:133], off
	global_load_dwordx4 v[200:203], v[132:133], off offset:16
	global_load_dwordx4 v[204:207], v[134:135], off
	global_load_dwordx4 v[208:211], v[134:135], off offset:16
	v_lshl_add_u64 v[132:133], v[132:133], 0, s[16:17]
	v_lshl_add_u64 v[134:135], v[134:135], 0, s[16:17]
	s_waitcnt vmcnt(12)
	v_pk_mul_f32 v[246:247], v[54:55], v[224:225]
	v_pk_mul_f32 v[248:249], v[52:53], v[222:223]
	v_pk_mul_f32 v[250:251], v[50:51], v[228:229]
	v_pk_mul_f32 v[252:253], v[48:49], v[226:227]
	v_pk_mul_f32 v[224:225], v[62:63], v[224:225]
	v_pk_mul_f32 v[222:223], v[60:61], v[222:223]
	v_pk_mul_f32 v[228:229], v[58:59], v[228:229]
	v_pk_mul_f32 v[226:227], v[56:57], v[226:227]
	v_pk_fma_f32 v[246:247], v[62:63], v[216:217], v[246:247] neg_lo:[0,0,1] neg_hi:[0,0,1]
	v_pk_fma_f32 v[248:249], v[60:61], v[214:215], v[248:249] neg_lo:[0,0,1] neg_hi:[0,0,1]
	v_pk_fma_f32 v[250:251], v[58:59], v[220:221], v[250:251] neg_lo:[0,0,1] neg_hi:[0,0,1]
	v_pk_fma_f32 v[252:253], v[56:57], v[218:219], v[252:253] neg_lo:[0,0,1] neg_hi:[0,0,1]
	v_pk_fma_f32 v[216:217], v[54:55], v[216:217], v[224:225]
	v_pk_fma_f32 v[214:215], v[52:53], v[214:215], v[222:223]
	v_pk_fma_f32 v[220:221], v[50:51], v[220:221], v[228:229]
	v_pk_fma_f32 v[218:219], v[48:49], v[218:219], v[226:227]
	v_cvt_pk_bf16_f32 v222, v248, v249
	v_cvt_pk_bf16_f32 v223, v246, v247
	v_cvt_pk_bf16_f32 v224, v252, v253
	v_cvt_pk_bf16_f32 v225, v250, v251
	v_cvt_pk_bf16_f32 v226, v214, v215
	v_cvt_pk_bf16_f32 v227, v216, v217
	v_cvt_pk_bf16_f32 v228, v218, v219
	v_cvt_pk_bf16_f32 v229, v220, v221
	global_store_dwordx4 v[190:191], v[222:225], off
	global_store_dwordx4 v[192:193], v[226:229], off
	v_lshl_add_u64 v[190:191], v[190:191], 0, s[14:15]
	v_lshl_add_u64 v[192:193], v[192:193], 0, s[14:15]
	global_load_dwordx4 v[214:217], v[132:133], off
	global_load_dwordx4 v[218:221], v[132:133], off offset:16
	global_load_dwordx4 v[222:225], v[134:135], off
	global_load_dwordx4 v[226:229], v[134:135], off offset:16
	s_waitcnt vmcnt(12)
	v_pk_mul_f32 v[246:247], v[38:39], v[240:241]
	v_pk_mul_f32 v[248:249], v[36:37], v[238:239]
	v_pk_mul_f32 v[250:251], v[34:35], v[244:245]
	v_pk_mul_f32 v[252:253], v[32:33], v[242:243]
	v_pk_mul_f32 v[240:241], v[46:47], v[240:241]
	v_pk_mul_f32 v[238:239], v[44:45], v[238:239]
	v_pk_mul_f32 v[244:245], v[42:43], v[244:245]
	v_pk_mul_f32 v[242:243], v[40:41], v[242:243]
	v_pk_fma_f32 v[246:247], v[46:47], v[232:233], v[246:247] neg_lo:[0,0,1] neg_hi:[0,0,1]
	v_pk_fma_f32 v[248:249], v[44:45], v[230:231], v[248:249] neg_lo:[0,0,1] neg_hi:[0,0,1]
	v_pk_fma_f32 v[250:251], v[42:43], v[236:237], v[250:251] neg_lo:[0,0,1] neg_hi:[0,0,1]
	v_pk_fma_f32 v[252:253], v[40:41], v[234:235], v[252:253] neg_lo:[0,0,1] neg_hi:[0,0,1]
	v_pk_fma_f32 v[232:233], v[38:39], v[232:233], v[240:241]
	v_pk_fma_f32 v[230:231], v[36:37], v[230:231], v[238:239]
	v_pk_fma_f32 v[236:237], v[34:35], v[236:237], v[244:245]
	v_pk_fma_f32 v[234:235], v[32:33], v[234:235], v[242:243]
	v_cvt_pk_bf16_f32 v238, v248, v249
	v_cvt_pk_bf16_f32 v239, v246, v247
	v_cvt_pk_bf16_f32 v240, v252, v253
	v_cvt_pk_bf16_f32 v241, v250, v251
	v_cvt_pk_bf16_f32 v242, v230, v231
	v_cvt_pk_bf16_f32 v243, v232, v233
	v_cvt_pk_bf16_f32 v244, v234, v235
	v_cvt_pk_bf16_f32 v245, v236, v237
	global_store_dwordx4 v[190:191], v[238:241], off
	global_store_dwordx4 v[192:193], v[242:245], off
	v_lshl_add_u64 v[190:191], v[190:191], 0, s[18:19]
	v_lshl_add_u64 v[192:193], v[192:193], 0, s[18:19]
	s_waitcnt vmcnt(8)
	v_pk_mul_f32 v[246:247], v[22:23], v[206:207]
	v_pk_mul_f32 v[248:249], v[20:21], v[204:205]
	v_pk_mul_f32 v[250:251], v[18:19], v[210:211]
	v_pk_mul_f32 v[252:253], v[16:17], v[208:209]
	v_pk_mul_f32 v[206:207], v[30:31], v[206:207]
	v_pk_mul_f32 v[204:205], v[28:29], v[204:205]
	v_pk_mul_f32 v[210:211], v[26:27], v[210:211]
	v_pk_mul_f32 v[208:209], v[24:25], v[208:209]
	v_pk_fma_f32 v[246:247], v[30:31], v[198:199], v[246:247] neg_lo:[0,0,1] neg_hi:[0,0,1]
	v_pk_fma_f32 v[248:249], v[28:29], v[196:197], v[248:249] neg_lo:[0,0,1] neg_hi:[0,0,1]
	v_pk_fma_f32 v[250:251], v[26:27], v[202:203], v[250:251] neg_lo:[0,0,1] neg_hi:[0,0,1]
	v_pk_fma_f32 v[252:253], v[24:25], v[200:201], v[252:253] neg_lo:[0,0,1] neg_hi:[0,0,1]
	v_pk_fma_f32 v[198:199], v[22:23], v[198:199], v[206:207]
	v_pk_fma_f32 v[196:197], v[20:21], v[196:197], v[204:205]
	v_pk_fma_f32 v[202:203], v[18:19], v[202:203], v[210:211]
	v_pk_fma_f32 v[200:201], v[16:17], v[200:201], v[208:209]
	v_cvt_pk_bf16_f32 v204, v248, v249
	v_cvt_pk_bf16_f32 v205, v246, v247
	v_cvt_pk_bf16_f32 v206, v252, v253
	v_cvt_pk_bf16_f32 v207, v250, v251
	v_cvt_pk_bf16_f32 v208, v196, v197
	v_cvt_pk_bf16_f32 v209, v198, v199
	v_cvt_pk_bf16_f32 v210, v200, v201
	v_cvt_pk_bf16_f32 v211, v202, v203
	global_store_dwordx4 v[190:191], v[204:207], off
	global_store_dwordx4 v[192:193], v[208:211], off
	v_lshl_add_u64 v[190:191], v[190:191], 0, s[14:15]
	v_lshl_add_u64 v[192:193], v[192:193], 0, s[14:15]
	s_waitcnt vmcnt(4)
	v_pk_mul_f32 v[246:247], v[6:7], v[224:225]
	v_pk_mul_f32 v[248:249], v[4:5], v[222:223]
	v_pk_mul_f32 v[250:251], v[2:3], v[228:229]
	v_pk_mul_f32 v[252:253], v[0:1], v[226:227]
	v_pk_mul_f32 v[224:225], v[14:15], v[224:225]
	v_pk_mul_f32 v[222:223], v[12:13], v[222:223]
	v_pk_mul_f32 v[228:229], v[10:11], v[228:229]
	v_pk_mul_f32 v[226:227], v[8:9], v[226:227]
	v_pk_fma_f32 v[246:247], v[14:15], v[216:217], v[246:247] neg_lo:[0,0,1] neg_hi:[0,0,1]
	v_pk_fma_f32 v[248:249], v[12:13], v[214:215], v[248:249] neg_lo:[0,0,1] neg_hi:[0,0,1]
	v_pk_fma_f32 v[250:251], v[10:11], v[220:221], v[250:251] neg_lo:[0,0,1] neg_hi:[0,0,1]
	v_pk_fma_f32 v[252:253], v[8:9], v[218:219], v[252:253] neg_lo:[0,0,1] neg_hi:[0,0,1]
	v_pk_fma_f32 v[216:217], v[6:7], v[216:217], v[224:225]
	v_pk_fma_f32 v[214:215], v[4:5], v[214:215], v[222:223]
	v_pk_fma_f32 v[220:221], v[2:3], v[220:221], v[228:229]
	v_pk_fma_f32 v[218:219], v[0:1], v[218:219], v[226:227]
	v_cvt_pk_bf16_f32 v222, v248, v249
	v_cvt_pk_bf16_f32 v223, v246, v247
	v_cvt_pk_bf16_f32 v224, v252, v253
	v_cvt_pk_bf16_f32 v225, v250, v251
	v_cvt_pk_bf16_f32 v226, v214, v215
	v_cvt_pk_bf16_f32 v227, v216, v217
	v_cvt_pk_bf16_f32 v228, v218, v219
	v_cvt_pk_bf16_f32 v229, v220, v221
	global_store_dwordx4 v[190:191], v[222:225], off
	global_store_dwordx4 v[192:193], v[226:229], off
.LBB0_1524:
	s_andn2_b64 vcc, exec, s[4:5]
	s_cbranch_vccnz .LBB0_1526
	s_or_b32 s0, s0, s29
	s_or_b32 s4, s0, s57
	s_ashr_i32 s5, s4, 31
	s_lshl_b64 s[4:5], s[4:5], 21
	v_add_u32_e32 v144, s27, v146
	s_add_u32 s4, s96, s4
	v_lshlrev_b64 v[182:183], 8, v[144:145]
	s_addc_u32 s5, s88, s5
	v_mov_b32_e32 v167, v145
	v_lshl_add_u64 v[182:183], s[4:5], 0, v[182:183]
	v_lshl_add_u64 v[182:183], v[182:183], 0, v[166:167]
	v_lshl_add_u64 v[184:185], v[182:183], 0, s[16:17]
	global_load_dwordx4 v[196:199], v[132:133], off
	global_load_dwordx4 v[200:203], v[132:133], off offset:16
	global_load_dwordx4 v[204:207], v[134:135], off
	global_load_dwordx4 v[208:211], v[134:135], off offset:16
	v_lshl_add_u64 v[132:133], v[132:133], 0, s[16:17]
	v_lshl_add_u64 v[134:135], v[134:135], 0, s[16:17]
	global_load_dwordx4 v[214:217], v[132:133], off
	global_load_dwordx4 v[218:221], v[132:133], off offset:16
	global_load_dwordx4 v[222:225], v[134:135], off
	global_load_dwordx4 v[226:229], v[134:135], off offset:16
	v_lshl_add_u64 v[132:133], v[132:133], 0, s[16:17]
	v_lshl_add_u64 v[134:135], v[134:135], 0, s[16:17]
	global_load_dwordx4 v[230:233], v[132:133], off
	global_load_dwordx4 v[234:237], v[132:133], off offset:16
	global_load_dwordx4 v[238:241], v[134:135], off
	global_load_dwordx4 v[242:245], v[134:135], off offset:16
	v_lshl_add_u64 v[132:133], v[132:133], 0, s[16:17]
	v_lshl_add_u64 v[134:135], v[134:135], 0, s[16:17]
	s_waitcnt vmcnt(8)
	v_pk_mul_f32 v[246:247], v[118:119], v[206:207]
	v_pk_mul_f32 v[248:249], v[116:117], v[204:205]
	v_pk_mul_f32 v[250:251], v[114:115], v[210:211]
	v_pk_mul_f32 v[252:253], v[112:113], v[208:209]
	v_pk_mul_f32 v[206:207], v[126:127], v[206:207]
	v_pk_mul_f32 v[204:205], v[124:125], v[204:205]
	v_pk_mul_f32 v[210:211], v[122:123], v[210:211]
	v_pk_mul_f32 v[208:209], v[120:121], v[208:209]
	v_pk_fma_f32 v[246:247], v[126:127], v[198:199], v[246:247] neg_lo:[0,0,1] neg_hi:[0,0,1]
	v_pk_fma_f32 v[248:249], v[124:125], v[196:197], v[248:249] neg_lo:[0,0,1] neg_hi:[0,0,1]
	v_pk_fma_f32 v[250:251], v[122:123], v[202:203], v[250:251] neg_lo:[0,0,1] neg_hi:[0,0,1]
	v_pk_fma_f32 v[252:253], v[120:121], v[200:201], v[252:253] neg_lo:[0,0,1] neg_hi:[0,0,1]
	v_pk_fma_f32 v[198:199], v[118:119], v[198:199], v[206:207]
	v_pk_fma_f32 v[196:197], v[116:117], v[196:197], v[204:205]
	v_pk_fma_f32 v[202:203], v[114:115], v[202:203], v[210:211]
	v_pk_fma_f32 v[200:201], v[112:113], v[200:201], v[208:209]
	v_pk_mul_f32 v[246:247], v[246:247], s[24:25] op_sel_hi:[1,0]
	v_pk_mul_f32 v[248:249], v[248:249], s[24:25] op_sel_hi:[1,0]
	v_pk_mul_f32 v[250:251], v[250:251], s[24:25] op_sel_hi:[1,0]
	v_pk_mul_f32 v[252:253], v[252:253], s[24:25] op_sel_hi:[1,0]
	v_pk_mul_f32 v[198:199], v[198:199], s[24:25] op_sel_hi:[1,0]
	v_pk_mul_f32 v[196:197], v[196:197], s[24:25] op_sel_hi:[1,0]
	v_pk_mul_f32 v[202:203], v[202:203], s[24:25] op_sel_hi:[1,0]
	v_pk_mul_f32 v[200:201], v[200:201], s[24:25] op_sel_hi:[1,0]
	v_cvt_pk_bf16_f32 v204, v248, v249
	v_cvt_pk_bf16_f32 v205, v246, v247
	v_cvt_pk_bf16_f32 v206, v252, v253
	v_cvt_pk_bf16_f32 v207, v250, v251
	v_cvt_pk_bf16_f32 v208, v196, v197
	v_cvt_pk_bf16_f32 v209, v198, v199
	v_cvt_pk_bf16_f32 v210, v200, v201
	v_cvt_pk_bf16_f32 v211, v202, v203
	global_store_dwordx4 v[182:183], v[204:207], off
	global_store_dwordx4 v[182:183], v[208:211], off offset:128
	v_lshl_add_u64 v[182:183], v[182:183], 0, s[16:17]
	global_load_dwordx4 v[196:199], v[132:133], off
	global_load_dwordx4 v[200:203], v[132:133], off offset:16
	global_load_dwordx4 v[204:207], v[134:135], off
	global_load_dwordx4 v[208:211], v[134:135], off offset:16
	v_lshl_add_u64 v[132:133], v[132:133], 0, s[22:23]
	v_lshl_add_u64 v[134:135], v[134:135], 0, s[22:23]
	s_waitcnt vmcnt(10)
	v_pk_mul_f32 v[246:247], v[102:103], v[224:225]
	v_pk_mul_f32 v[248:249], v[100:101], v[222:223]
	v_pk_mul_f32 v[250:251], v[98:99], v[228:229]
	v_pk_mul_f32 v[252:253], v[96:97], v[226:227]
	v_pk_mul_f32 v[224:225], v[110:111], v[224:225]
	v_pk_mul_f32 v[222:223], v[108:109], v[222:223]
	v_pk_mul_f32 v[228:229], v[106:107], v[228:229]
	v_pk_mul_f32 v[226:227], v[104:105], v[226:227]
	v_pk_fma_f32 v[246:247], v[110:111], v[216:217], v[246:247] neg_lo:[0,0,1] neg_hi:[0,0,1]
	v_pk_fma_f32 v[248:249], v[108:109], v[214:215], v[248:249] neg_lo:[0,0,1] neg_hi:[0,0,1]
	v_pk_fma_f32 v[250:251], v[106:107], v[220:221], v[250:251] neg_lo:[0,0,1] neg_hi:[0,0,1]
	v_pk_fma_f32 v[252:253], v[104:105], v[218:219], v[252:253] neg_lo:[0,0,1] neg_hi:[0,0,1]
	v_pk_fma_f32 v[216:217], v[102:103], v[216:217], v[224:225]
	v_pk_fma_f32 v[214:215], v[100:101], v[214:215], v[222:223]
	v_pk_fma_f32 v[220:221], v[98:99], v[220:221], v[228:229]
	v_pk_fma_f32 v[218:219], v[96:97], v[218:219], v[226:227]
	v_pk_mul_f32 v[246:247], v[246:247], s[24:25] op_sel_hi:[1,0]
	v_pk_mul_f32 v[248:249], v[248:249], s[24:25] op_sel_hi:[1,0]
	v_pk_mul_f32 v[250:251], v[250:251], s[24:25] op_sel_hi:[1,0]
	v_pk_mul_f32 v[252:253], v[252:253], s[24:25] op_sel_hi:[1,0]
	v_pk_mul_f32 v[216:217], v[216:217], s[24:25] op_sel_hi:[1,0]
	v_pk_mul_f32 v[214:215], v[214:215], s[24:25] op_sel_hi:[1,0]
	v_pk_mul_f32 v[220:221], v[220:221], s[24:25] op_sel_hi:[1,0]
	v_pk_mul_f32 v[218:219], v[218:219], s[24:25] op_sel_hi:[1,0]
	v_cvt_pk_bf16_f32 v222, v248, v249
	v_cvt_pk_bf16_f32 v223, v246, v247
	v_cvt_pk_bf16_f32 v224, v252, v253
	v_cvt_pk_bf16_f32 v225, v250, v251
	v_cvt_pk_bf16_f32 v226, v214, v215
	v_cvt_pk_bf16_f32 v227, v216, v217
	v_cvt_pk_bf16_f32 v228, v218, v219
	v_cvt_pk_bf16_f32 v229, v220, v221
	global_store_dwordx4 v[182:183], v[222:225], off
	global_store_dwordx4 v[182:183], v[226:229], off offset:128
	v_lshl_add_u64 v[182:183], v[182:183], 0, s[16:17]
	global_load_dwordx4 v[214:217], v[132:133], off
	global_load_dwordx4 v[218:221], v[132:133], off offset:16
	global_load_dwordx4 v[222:225], v[134:135], off
	global_load_dwordx4 v[226:229], v[134:135], off offset:16
	v_lshl_add_u64 v[132:133], v[132:133], 0, s[16:17]
	v_lshl_add_u64 v[134:135], v[134:135], 0, s[16:17]
	s_waitcnt vmcnt(12)
	v_pk_mul_f32 v[246:247], v[86:87], v[240:241]
	v_pk_mul_f32 v[248:249], v[84:85], v[238:239]
	v_pk_mul_f32 v[250:251], v[82:83], v[244:245]
	v_pk_mul_f32 v[252:253], v[80:81], v[242:243]
	v_pk_mul_f32 v[240:241], v[94:95], v[240:241]
	v_pk_mul_f32 v[238:239], v[92:93], v[238:239]
	v_pk_mul_f32 v[244:245], v[90:91], v[244:245]
	v_pk_mul_f32 v[242:243], v[88:89], v[242:243]
	v_pk_fma_f32 v[246:247], v[94:95], v[232:233], v[246:247] neg_lo:[0,0,1] neg_hi:[0,0,1]
	v_pk_fma_f32 v[248:249], v[92:93], v[230:231], v[248:249] neg_lo:[0,0,1] neg_hi:[0,0,1]
	v_pk_fma_f32 v[250:251], v[90:91], v[236:237], v[250:251] neg_lo:[0,0,1] neg_hi:[0,0,1]
	v_pk_fma_f32 v[252:253], v[88:89], v[234:235], v[252:253] neg_lo:[0,0,1] neg_hi:[0,0,1]
	v_pk_fma_f32 v[232:233], v[86:87], v[232:233], v[240:241]
	v_pk_fma_f32 v[230:231], v[84:85], v[230:231], v[238:239]
	v_pk_fma_f32 v[236:237], v[82:83], v[236:237], v[244:245]
	v_pk_fma_f32 v[234:235], v[80:81], v[234:235], v[242:243]
	v_pk_mul_f32 v[246:247], v[246:247], s[24:25] op_sel_hi:[1,0]
	v_pk_mul_f32 v[248:249], v[248:249], s[24:25] op_sel_hi:[1,0]
	v_pk_mul_f32 v[250:251], v[250:251], s[24:25] op_sel_hi:[1,0]
	v_pk_mul_f32 v[252:253], v[252:253], s[24:25] op_sel_hi:[1,0]
	v_pk_mul_f32 v[232:233], v[232:233], s[24:25] op_sel_hi:[1,0]
	v_pk_mul_f32 v[230:231], v[230:231], s[24:25] op_sel_hi:[1,0]
	v_pk_mul_f32 v[236:237], v[236:237], s[24:25] op_sel_hi:[1,0]
	v_pk_mul_f32 v[234:235], v[234:235], s[24:25] op_sel_hi:[1,0]
	v_cvt_pk_bf16_f32 v238, v248, v249
	v_cvt_pk_bf16_f32 v239, v246, v247
	v_cvt_pk_bf16_f32 v240, v252, v253
	v_cvt_pk_bf16_f32 v241, v250, v251
	v_cvt_pk_bf16_f32 v242, v230, v231
	v_cvt_pk_bf16_f32 v243, v232, v233
	v_cvt_pk_bf16_f32 v244, v234, v235
	v_cvt_pk_bf16_f32 v245, v236, v237
	global_store_dwordx4 v[182:183], v[238:241], off
	global_store_dwordx4 v[182:183], v[242:245], off offset:128
	v_lshl_add_u64 v[182:183], v[182:183], 0, s[16:17]
	global_load_dwordx4 v[230:233], v[132:133], off
	global_load_dwordx4 v[234:237], v[132:133], off offset:16
	global_load_dwordx4 v[238:241], v[134:135], off
	global_load_dwordx4 v[242:245], v[134:135], off offset:16
	v_lshl_add_u64 v[132:133], v[132:133], 0, s[16:17]
	v_lshl_add_u64 v[134:135], v[134:135], 0, s[16:17]
	s_waitcnt vmcnt(12)
	v_pk_mul_f32 v[246:247], v[70:71], v[206:207]
	v_pk_mul_f32 v[248:249], v[68:69], v[204:205]
	v_pk_mul_f32 v[250:251], v[66:67], v[210:211]
	v_pk_mul_f32 v[252:253], v[64:65], v[208:209]
	v_pk_mul_f32 v[206:207], v[78:79], v[206:207]
	v_pk_mul_f32 v[204:205], v[76:77], v[204:205]
	v_pk_mul_f32 v[210:211], v[74:75], v[210:211]
	v_pk_mul_f32 v[208:209], v[72:73], v[208:209]
	v_pk_fma_f32 v[246:247], v[78:79], v[198:199], v[246:247] neg_lo:[0,0,1] neg_hi:[0,0,1]
	v_pk_fma_f32 v[248:249], v[76:77], v[196:197], v[248:249] neg_lo:[0,0,1] neg_hi:[0,0,1]
	v_pk_fma_f32 v[250:251], v[74:75], v[202:203], v[250:251] neg_lo:[0,0,1] neg_hi:[0,0,1]
	v_pk_fma_f32 v[252:253], v[72:73], v[200:201], v[252:253] neg_lo:[0,0,1] neg_hi:[0,0,1]
	v_pk_fma_f32 v[198:199], v[70:71], v[198:199], v[206:207]
	v_pk_fma_f32 v[196:197], v[68:69], v[196:197], v[204:205]
	v_pk_fma_f32 v[202:203], v[66:67], v[202:203], v[210:211]
	v_pk_fma_f32 v[200:201], v[64:65], v[200:201], v[208:209]
	v_pk_mul_f32 v[246:247], v[246:247], s[24:25] op_sel_hi:[1,0]
	v_pk_mul_f32 v[248:249], v[248:249], s[24:25] op_sel_hi:[1,0]
	v_pk_mul_f32 v[250:251], v[250:251], s[24:25] op_sel_hi:[1,0]
	v_pk_mul_f32 v[252:253], v[252:253], s[24:25] op_sel_hi:[1,0]
	v_pk_mul_f32 v[198:199], v[198:199], s[24:25] op_sel_hi:[1,0]
	v_pk_mul_f32 v[196:197], v[196:197], s[24:25] op_sel_hi:[1,0]
	v_pk_mul_f32 v[202:203], v[202:203], s[24:25] op_sel_hi:[1,0]
	v_pk_mul_f32 v[200:201], v[200:201], s[24:25] op_sel_hi:[1,0]
	v_cvt_pk_bf16_f32 v204, v248, v249
	v_cvt_pk_bf16_f32 v205, v246, v247
	v_cvt_pk_bf16_f32 v206, v252, v253
	v_cvt_pk_bf16_f32 v207, v250, v251
	v_cvt_pk_bf16_f32 v208, v196, v197
	v_cvt_pk_bf16_f32 v209, v198, v199
	v_cvt_pk_bf16_f32 v210, v200, v201
	v_cvt_pk_bf16_f32 v211, v202, v203
	global_store_dwordx4 v[182:183], v[204:207], off
	global_store_dwordx4 v[182:183], v[208:211], off offset:128
	v_lshl_add_u64 v[182:183], v[182:183], 0, s[22:23]
	global_load_dwordx4 v[196:199], v[132:133], off
	global_load_dwordx4 v[200:203], v[132:133], off offset:16
	global_load_dwordx4 v[204:207], v[134:135], off
	global_load_dwordx4 v[208:211], v[134:135], off offset:16
	v_lshl_add_u64 v[132:133], v[132:133], 0, s[16:17]
	v_lshl_add_u64 v[134:135], v[134:135], 0, s[16:17]
	s_waitcnt vmcnt(12)
	v_pk_mul_f32 v[246:247], v[54:55], v[224:225]
	v_pk_mul_f32 v[248:249], v[52:53], v[222:223]
	v_pk_mul_f32 v[250:251], v[50:51], v[228:229]
	v_pk_mul_f32 v[252:253], v[48:49], v[226:227]
	v_pk_mul_f32 v[224:225], v[62:63], v[224:225]
	v_pk_mul_f32 v[222:223], v[60:61], v[222:223]
	v_pk_mul_f32 v[228:229], v[58:59], v[228:229]
	v_pk_mul_f32 v[226:227], v[56:57], v[226:227]
	v_pk_fma_f32 v[246:247], v[62:63], v[216:217], v[246:247] neg_lo:[0,0,1] neg_hi:[0,0,1]
	v_pk_fma_f32 v[248:249], v[60:61], v[214:215], v[248:249] neg_lo:[0,0,1] neg_hi:[0,0,1]
	v_pk_fma_f32 v[250:251], v[58:59], v[220:221], v[250:251] neg_lo:[0,0,1] neg_hi:[0,0,1]
	v_pk_fma_f32 v[252:253], v[56:57], v[218:219], v[252:253] neg_lo:[0,0,1] neg_hi:[0,0,1]
	v_pk_fma_f32 v[216:217], v[54:55], v[216:217], v[224:225]
	v_pk_fma_f32 v[214:215], v[52:53], v[214:215], v[222:223]
	v_pk_fma_f32 v[220:221], v[50:51], v[220:221], v[228:229]
	v_pk_fma_f32 v[218:219], v[48:49], v[218:219], v[226:227]
	v_pk_mul_f32 v[246:247], v[246:247], s[24:25] op_sel_hi:[1,0]
	v_pk_mul_f32 v[248:249], v[248:249], s[24:25] op_sel_hi:[1,0]
	v_pk_mul_f32 v[250:251], v[250:251], s[24:25] op_sel_hi:[1,0]
	v_pk_mul_f32 v[252:253], v[252:253], s[24:25] op_sel_hi:[1,0]
	v_pk_mul_f32 v[216:217], v[216:217], s[24:25] op_sel_hi:[1,0]
	v_pk_mul_f32 v[214:215], v[214:215], s[24:25] op_sel_hi:[1,0]
	v_pk_mul_f32 v[220:221], v[220:221], s[24:25] op_sel_hi:[1,0]
	v_pk_mul_f32 v[218:219], v[218:219], s[24:25] op_sel_hi:[1,0]
	v_cvt_pk_bf16_f32 v222, v248, v249
	v_cvt_pk_bf16_f32 v223, v246, v247
	v_cvt_pk_bf16_f32 v224, v252, v253
	v_cvt_pk_bf16_f32 v225, v250, v251
	v_cvt_pk_bf16_f32 v226, v214, v215
	v_cvt_pk_bf16_f32 v227, v216, v217
	v_cvt_pk_bf16_f32 v228, v218, v219
	v_cvt_pk_bf16_f32 v229, v220, v221
	global_store_dwordx4 v[182:183], v[222:225], off
	global_store_dwordx4 v[182:183], v[226:229], off offset:128
	v_lshl_add_u64 v[182:183], v[182:183], 0, s[16:17]
	global_load_dwordx4 v[214:217], v[132:133], off
	global_load_dwordx4 v[218:221], v[132:133], off offset:16
	global_load_dwordx4 v[222:225], v[134:135], off
	global_load_dwordx4 v[226:229], v[134:135], off offset:16
	s_waitcnt vmcnt(12)
	v_pk_mul_f32 v[246:247], v[38:39], v[240:241]
	v_pk_mul_f32 v[248:249], v[36:37], v[238:239]
	v_pk_mul_f32 v[250:251], v[34:35], v[244:245]
	v_pk_mul_f32 v[252:253], v[32:33], v[242:243]
	v_pk_mul_f32 v[240:241], v[46:47], v[240:241]
	v_pk_mul_f32 v[238:239], v[44:45], v[238:239]
	v_pk_mul_f32 v[244:245], v[42:43], v[244:245]
	v_pk_mul_f32 v[242:243], v[40:41], v[242:243]
	v_pk_fma_f32 v[246:247], v[46:47], v[232:233], v[246:247] neg_lo:[0,0,1] neg_hi:[0,0,1]
	v_pk_fma_f32 v[248:249], v[44:45], v[230:231], v[248:249] neg_lo:[0,0,1] neg_hi:[0,0,1]
	v_pk_fma_f32 v[250:251], v[42:43], v[236:237], v[250:251] neg_lo:[0,0,1] neg_hi:[0,0,1]
	v_pk_fma_f32 v[252:253], v[40:41], v[234:235], v[252:253] neg_lo:[0,0,1] neg_hi:[0,0,1]
	v_pk_fma_f32 v[232:233], v[38:39], v[232:233], v[240:241]
	v_pk_fma_f32 v[230:231], v[36:37], v[230:231], v[238:239]
	v_pk_fma_f32 v[236:237], v[34:35], v[236:237], v[244:245]
	v_pk_fma_f32 v[234:235], v[32:33], v[234:235], v[242:243]
	v_pk_mul_f32 v[246:247], v[246:247], s[24:25] op_sel_hi:[1,0]
	v_pk_mul_f32 v[248:249], v[248:249], s[24:25] op_sel_hi:[1,0]
	v_pk_mul_f32 v[250:251], v[250:251], s[24:25] op_sel_hi:[1,0]
	v_pk_mul_f32 v[252:253], v[252:253], s[24:25] op_sel_hi:[1,0]
	v_pk_mul_f32 v[232:233], v[232:233], s[24:25] op_sel_hi:[1,0]
	v_pk_mul_f32 v[230:231], v[230:231], s[24:25] op_sel_hi:[1,0]
	v_pk_mul_f32 v[236:237], v[236:237], s[24:25] op_sel_hi:[1,0]
	v_pk_mul_f32 v[234:235], v[234:235], s[24:25] op_sel_hi:[1,0]
	v_cvt_pk_bf16_f32 v238, v248, v249
	v_cvt_pk_bf16_f32 v239, v246, v247
	v_cvt_pk_bf16_f32 v240, v252, v253
	v_cvt_pk_bf16_f32 v241, v250, v251
	v_cvt_pk_bf16_f32 v242, v230, v231
	v_cvt_pk_bf16_f32 v243, v232, v233
	v_cvt_pk_bf16_f32 v244, v234, v235
	v_cvt_pk_bf16_f32 v245, v236, v237
	global_store_dwordx4 v[182:183], v[238:241], off
	global_store_dwordx4 v[182:183], v[242:245], off offset:128
	v_lshl_add_u64 v[182:183], v[182:183], 0, s[16:17]
	s_waitcnt vmcnt(8)
	v_pk_mul_f32 v[246:247], v[22:23], v[206:207]
	v_pk_mul_f32 v[248:249], v[20:21], v[204:205]
	v_pk_mul_f32 v[250:251], v[18:19], v[210:211]
	v_pk_mul_f32 v[252:253], v[16:17], v[208:209]
	v_pk_mul_f32 v[206:207], v[30:31], v[206:207]
	v_pk_mul_f32 v[204:205], v[28:29], v[204:205]
	v_pk_mul_f32 v[210:211], v[26:27], v[210:211]
	v_pk_mul_f32 v[208:209], v[24:25], v[208:209]
	v_pk_fma_f32 v[246:247], v[30:31], v[198:199], v[246:247] neg_lo:[0,0,1] neg_hi:[0,0,1]
	v_pk_fma_f32 v[248:249], v[28:29], v[196:197], v[248:249] neg_lo:[0,0,1] neg_hi:[0,0,1]
	v_pk_fma_f32 v[250:251], v[26:27], v[202:203], v[250:251] neg_lo:[0,0,1] neg_hi:[0,0,1]
	v_pk_fma_f32 v[252:253], v[24:25], v[200:201], v[252:253] neg_lo:[0,0,1] neg_hi:[0,0,1]
	v_pk_fma_f32 v[198:199], v[22:23], v[198:199], v[206:207]
	v_pk_fma_f32 v[196:197], v[20:21], v[196:197], v[204:205]
	v_pk_fma_f32 v[202:203], v[18:19], v[202:203], v[210:211]
	v_pk_fma_f32 v[200:201], v[16:17], v[200:201], v[208:209]
	v_pk_mul_f32 v[246:247], v[246:247], s[24:25] op_sel_hi:[1,0]
	v_pk_mul_f32 v[248:249], v[248:249], s[24:25] op_sel_hi:[1,0]
	v_pk_mul_f32 v[250:251], v[250:251], s[24:25] op_sel_hi:[1,0]
	v_pk_mul_f32 v[252:253], v[252:253], s[24:25] op_sel_hi:[1,0]
	v_pk_mul_f32 v[198:199], v[198:199], s[24:25] op_sel_hi:[1,0]
	v_pk_mul_f32 v[196:197], v[196:197], s[24:25] op_sel_hi:[1,0]
	v_pk_mul_f32 v[202:203], v[202:203], s[24:25] op_sel_hi:[1,0]
	v_pk_mul_f32 v[200:201], v[200:201], s[24:25] op_sel_hi:[1,0]
	v_cvt_pk_bf16_f32 v204, v248, v249
	v_cvt_pk_bf16_f32 v205, v246, v247
	v_cvt_pk_bf16_f32 v206, v252, v253
	v_cvt_pk_bf16_f32 v207, v250, v251
	v_cvt_pk_bf16_f32 v208, v196, v197
	v_cvt_pk_bf16_f32 v209, v198, v199
	v_cvt_pk_bf16_f32 v210, v200, v201
	v_cvt_pk_bf16_f32 v211, v202, v203
	global_store_dwordx4 v[182:183], v[204:207], off
	global_store_dwordx4 v[182:183], v[208:211], off offset:128
	v_lshl_add_u64 v[182:183], v[182:183], 0, s[16:17]
	s_waitcnt vmcnt(4)
	v_pk_mul_f32 v[246:247], v[6:7], v[224:225]
	v_pk_mul_f32 v[248:249], v[4:5], v[222:223]
	v_pk_mul_f32 v[250:251], v[2:3], v[228:229]
	v_pk_mul_f32 v[252:253], v[0:1], v[226:227]
	v_pk_mul_f32 v[224:225], v[14:15], v[224:225]
	v_pk_mul_f32 v[222:223], v[12:13], v[222:223]
	v_pk_mul_f32 v[228:229], v[10:11], v[228:229]
	v_pk_mul_f32 v[226:227], v[8:9], v[226:227]
	v_pk_fma_f32 v[246:247], v[14:15], v[216:217], v[246:247] neg_lo:[0,0,1] neg_hi:[0,0,1]
	v_pk_fma_f32 v[248:249], v[12:13], v[214:215], v[248:249] neg_lo:[0,0,1] neg_hi:[0,0,1]
	v_pk_fma_f32 v[250:251], v[10:11], v[220:221], v[250:251] neg_lo:[0,0,1] neg_hi:[0,0,1]
	v_pk_fma_f32 v[252:253], v[8:9], v[218:219], v[252:253] neg_lo:[0,0,1] neg_hi:[0,0,1]
	v_pk_fma_f32 v[216:217], v[6:7], v[216:217], v[224:225]
	v_pk_fma_f32 v[214:215], v[4:5], v[214:215], v[222:223]
	v_pk_fma_f32 v[220:221], v[2:3], v[220:221], v[228:229]
	v_pk_fma_f32 v[218:219], v[0:1], v[218:219], v[226:227]
	v_pk_mul_f32 v[246:247], v[246:247], s[24:25] op_sel_hi:[1,0]
	v_pk_mul_f32 v[248:249], v[248:249], s[24:25] op_sel_hi:[1,0]
	v_pk_mul_f32 v[250:251], v[250:251], s[24:25] op_sel_hi:[1,0]
	v_pk_mul_f32 v[252:253], v[252:253], s[24:25] op_sel_hi:[1,0]
	v_pk_mul_f32 v[216:217], v[216:217], s[24:25] op_sel_hi:[1,0]
	v_pk_mul_f32 v[214:215], v[214:215], s[24:25] op_sel_hi:[1,0]
	v_pk_mul_f32 v[220:221], v[220:221], s[24:25] op_sel_hi:[1,0]
	v_pk_mul_f32 v[218:219], v[218:219], s[24:25] op_sel_hi:[1,0]
	v_cvt_pk_bf16_f32 v222, v248, v249
	v_cvt_pk_bf16_f32 v223, v246, v247
	v_cvt_pk_bf16_f32 v224, v252, v253
	v_cvt_pk_bf16_f32 v225, v250, v251
	v_cvt_pk_bf16_f32 v226, v214, v215
	v_cvt_pk_bf16_f32 v227, v216, v217
	v_cvt_pk_bf16_f32 v228, v218, v219
	v_cvt_pk_bf16_f32 v229, v220, v221
	global_store_dwordx4 v[182:183], v[222:225], off
	global_store_dwordx4 v[182:183], v[226:229], off offset:128
